# GDN: staged lgkmcnt waits (5,4,3,2,0) so the dot products start when the first k/q vector lands
# speedup vs baseline: 1.0039x; 1.0039x over previous
.Lgd2_loop:
	global_load_dword v108, v36, s[8:9]
	global_load_dword v109, v36, s[8:9] offset:-2048
	global_load_dword v111, v104, s[8:9] offset:2048
	global_load_dword v110, v37, s[10:11]
	global_load_dword v112, v105, s[10:11]
	global_load_dword v113, v106, s[12:13]
	s_add_u32 s8, s8, 0xc000
	s_addc_u32 s9, s9, 0
	s_add_u32 s10, s10, 0x20000
	s_addc_u32 s11, s11, 0
	s_add_u32 s12, s12, 0x400
	s_addc_u32 s13, s13, 0
	s_waitcnt lgkmcnt(5)
	v_pk_mul_f32 v[38:39], v[6:7], v[56:57] op_sel_hi:[1,0]
	v_pk_mul_f32 v[40:41], v[6:7], v[56:57] op_sel:[0,1] op_sel_hi:[1,1]
	v_pk_fma_f32 v[38:39], v[8:9], v[58:59], v[38:39] op_sel_hi:[1,0,1]
	v_pk_fma_f32 v[40:41], v[8:9], v[58:59], v[40:41] op_sel:[0,1,0] op_sel_hi:[1,1,1]
	s_waitcnt lgkmcnt(4)
	v_pk_fma_f32 v[38:39], v[10:11], v[60:61], v[38:39] op_sel_hi:[1,0,1]
	v_pk_fma_f32 v[40:41], v[10:11], v[60:61], v[40:41] op_sel:[0,1,0] op_sel_hi:[1,1,1]
	v_pk_fma_f32 v[38:39], v[12:13], v[62:63], v[38:39] op_sel_hi:[1,0,1]
	v_pk_fma_f32 v[40:41], v[12:13], v[62:63], v[40:41] op_sel:[0,1,0] op_sel_hi:[1,1,1]
	s_waitcnt lgkmcnt(3)
	v_pk_fma_f32 v[38:39], v[14:15], v[64:65], v[38:39] op_sel_hi:[1,0,1]
	v_pk_fma_f32 v[40:41], v[14:15], v[64:65], v[40:41] op_sel:[0,1,0] op_sel_hi:[1,1,1]
	v_pk_fma_f32 v[38:39], v[16:17], v[66:67], v[38:39] op_sel_hi:[1,0,1]
	v_pk_fma_f32 v[40:41], v[16:17], v[66:67], v[40:41] op_sel:[0,1,0] op_sel_hi:[1,1,1]
	s_waitcnt lgkmcnt(2)
	v_pk_fma_f32 v[38:39], v[18:19], v[68:69], v[38:39] op_sel_hi:[1,0,1]
	v_pk_fma_f32 v[40:41], v[18:19], v[68:69], v[40:41] op_sel:[0,1,0] op_sel_hi:[1,1,1]
	v_pk_fma_f32 v[38:39], v[20:21], v[70:71], v[38:39] op_sel_hi:[1,0,1]
	v_pk_fma_f32 v[40:41], v[20:21], v[70:71], v[40:41] op_sel:[0,1,0] op_sel_hi:[1,1,1]
	s_waitcnt lgkmcnt(0)
	v_mul_f32_e32 v50, v76, v51
	v_add_f32_dpp v38, v38, v38 row_ror:8 row_mask:0xf bank_mask:0x3 bound_ctrl:1
	v_add_f32_dpp v39, v39, v39 row_ror:8 row_mask:0xf bank_mask:0x3 bound_ctrl:1
	v_add_f32_dpp v38, v40, v40 row_ror:8 row_mask:0xf bank_mask:0xc bound_ctrl:1
	v_add_f32_dpp v39, v41, v41 row_ror:8 row_mask:0xf bank_mask:0xc bound_ctrl:1
	ds_read_b128 v[80:83], v2 offset:1280
	v_add_f32_dpp v38, v38, v38 row_half_mirror row_mask:0xf bank_mask:0x5 bound_ctrl:1
	v_add_f32_dpp v38, v39, v39 row_half_mirror row_mask:0xf bank_mask:0xa bound_ctrl:1
	ds_read_b128 v[84:87], v2 offset:1536
	ds_read_b128 v[88:91], v2 offset:1792
	v_add_f32_dpp v38, v38, v38 quad_perm:[1,0,3,2] row_mask:0xf bank_mask:0xf bound_ctrl:1
	ds_read_b128 v[92:95], v2 offset:2048
	ds_read_b64 v[96:97], v3 offset:12800
	v_add_f32_dpp v38, v38, v38 quad_perm:[2,3,0,1] row_mask:0xf bank_mask:0xf bound_ctrl:1
	ds_read_b128 v[100:103], v1 offset:14608
	v_cmp_gt_f32_e32 vcc, 0x2b8cbccc, v50
	v_fmac_f32_dpp v72, -v38, v50 row_newbcast:0 row_mask:0xf bank_mask:0xf bound_ctrl:1
	v_fmac_f32_dpp v73, -v38, v50 row_newbcast:4 row_mask:0xf bank_mask:0xf bound_ctrl:1
	v_pk_mul_f32 v[44:45], v[72:73], v[76:77] op_sel:[0,1] op_sel_hi:[1,1]
	v_pk_mul_f32 v[48:49], v[44:45], v[78:79] op_sel_hi:[1,0]
	v_rcp_f32_e32 v52, v50
	s_add_u32 s14, s14, 0x1000
	s_addc_u32 s15, s15, 0
	v_fmac_f32_dpp v48, v38, v50 row_newbcast:8 row_mask:0xf bank_mask:0xf bound_ctrl:1
	v_fmac_f32_dpp v49, v38, v50 row_newbcast:12 row_mask:0xf bank_mask:0xf bound_ctrl:1
	s_cbranch_vccnz .Lgd2_rare0_0
.Lgd2_back0_0:
	v_cvt_pk_bf16_f32 v54, v48, v49
	v_pk_mul_f32 v[46:47], v[44:45], v[52:53] op_sel_hi:[1,0]
	v_pk_fma_f32 v[6:7], v[56:57], v[46:47], v[6:7] op_sel_hi:[0,1,1]
	v_pk_fma_f32 v[8:9], v[58:59], v[46:47], v[8:9] op_sel_hi:[0,1,1]
	v_pk_fma_f32 v[10:11], v[60:61], v[46:47], v[10:11] op_sel_hi:[0,1,1]
	v_pk_fma_f32 v[12:13], v[62:63], v[46:47], v[12:13] op_sel_hi:[0,1,1]
	v_pk_fma_f32 v[14:15], v[64:65], v[46:47], v[14:15] op_sel_hi:[0,1,1]
	v_pk_fma_f32 v[16:17], v[66:67], v[46:47], v[16:17] op_sel_hi:[0,1,1]
	v_pk_fma_f32 v[18:19], v[68:69], v[46:47], v[18:19] op_sel_hi:[0,1,1]
	v_pk_fma_f32 v[20:21], v[70:71], v[46:47], v[20:21] op_sel_hi:[0,1,1]
	global_store_dword v154, v54, s[14:15] offset:-4096
	s_waitcnt lgkmcnt(5)
	v_pk_mul_f32 v[38:39], v[6:7], v[80:81] op_sel_hi:[1,0]
	v_pk_mul_f32 v[40:41], v[6:7], v[80:81] op_sel:[0,1] op_sel_hi:[1,1]
	v_pk_fma_f32 v[38:39], v[8:9], v[82:83], v[38:39] op_sel_hi:[1,0,1]
	v_pk_fma_f32 v[40:41], v[8:9], v[82:83], v[40:41] op_sel:[0,1,0] op_sel_hi:[1,1,1]
	s_waitcnt lgkmcnt(4)
	v_pk_fma_f32 v[38:39], v[10:11], v[84:85], v[38:39] op_sel_hi:[1,0,1]
	v_pk_fma_f32 v[40:41], v[10:11], v[84:85], v[40:41] op_sel:[0,1,0] op_sel_hi:[1,1,1]
	v_pk_fma_f32 v[38:39], v[12:13], v[86:87], v[38:39] op_sel_hi:[1,0,1]
	v_pk_fma_f32 v[40:41], v[12:13], v[86:87], v[40:41] op_sel:[0,1,0] op_sel_hi:[1,1,1]
	s_waitcnt lgkmcnt(3)
	v_pk_fma_f32 v[38:39], v[14:15], v[88:89], v[38:39] op_sel_hi:[1,0,1]
	v_pk_fma_f32 v[40:41], v[14:15], v[88:89], v[40:41] op_sel:[0,1,0] op_sel_hi:[1,1,1]
	v_pk_fma_f32 v[38:39], v[16:17], v[90:91], v[38:39] op_sel_hi:[1,0,1]
	v_pk_fma_f32 v[40:41], v[16:17], v[90:91], v[40:41] op_sel:[0,1,0] op_sel_hi:[1,1,1]
	s_waitcnt lgkmcnt(2)
	v_pk_fma_f32 v[38:39], v[18:19], v[92:93], v[38:39] op_sel_hi:[1,0,1]
	v_pk_fma_f32 v[40:41], v[18:19], v[92:93], v[40:41] op_sel:[0,1,0] op_sel_hi:[1,1,1]
	v_pk_fma_f32 v[38:39], v[20:21], v[94:95], v[38:39] op_sel_hi:[1,0,1]
	v_pk_fma_f32 v[40:41], v[20:21], v[94:95], v[40:41] op_sel:[0,1,0] op_sel_hi:[1,1,1]
	s_waitcnt lgkmcnt(0)
	v_mul_f32_e32 v51, v100, v50
	v_add_f32_dpp v38, v38, v38 row_ror:8 row_mask:0xf bank_mask:0x3 bound_ctrl:1
	v_add_f32_dpp v39, v39, v39 row_ror:8 row_mask:0xf bank_mask:0x3 bound_ctrl:1
	v_add_f32_dpp v38, v40, v40 row_ror:8 row_mask:0xf bank_mask:0xc bound_ctrl:1
	v_add_f32_dpp v39, v41, v41 row_ror:8 row_mask:0xf bank_mask:0xc bound_ctrl:1
	ds_read_b128 v[56:59], v2 offset:2304
	v_add_f32_dpp v38, v38, v38 row_half_mirror row_mask:0xf bank_mask:0x5 bound_ctrl:1
	v_add_f32_dpp v38, v39, v39 row_half_mirror row_mask:0xf bank_mask:0xa bound_ctrl:1
	ds_read_b128 v[60:63], v2 offset:2560
	ds_read_b128 v[64:67], v2 offset:2816
	v_add_f32_dpp v38, v38, v38 quad_perm:[1,0,3,2] row_mask:0xf bank_mask:0xf bound_ctrl:1
	ds_read_b128 v[68:71], v2 offset:3072
	ds_read_b64 v[72:73], v3 offset:13056
	v_add_f32_dpp v38, v38, v38 quad_perm:[2,3,0,1] row_mask:0xf bank_mask:0xf bound_ctrl:1
	ds_read_b128 v[76:79], v1 offset:14624
	v_cmp_gt_f32_e32 vcc, 0x2b8cbccc, v51
	v_fmac_f32_dpp v96, -v38, v51 row_newbcast:0 row_mask:0xf bank_mask:0xf bound_ctrl:1
	v_fmac_f32_dpp v97, -v38, v51 row_newbcast:4 row_mask:0xf bank_mask:0xf bound_ctrl:1
	v_pk_mul_f32 v[44:45], v[96:97], v[100:101] op_sel:[0,1] op_sel_hi:[1,1]
	v_pk_mul_f32 v[48:49], v[44:45], v[102:103] op_sel_hi:[1,0]
	v_rcp_f32_e32 v52, v51
	s_add_u32 s14, s14, 0x1000
	s_addc_u32 s15, s15, 0
	v_fmac_f32_dpp v48, v38, v51 row_newbcast:8 row_mask:0xf bank_mask:0xf bound_ctrl:1
	v_fmac_f32_dpp v49, v38, v51 row_newbcast:12 row_mask:0xf bank_mask:0xf bound_ctrl:1
	s_cbranch_vccnz .Lgd2_rare0_1
.Lgd2_back0_1:
	v_cvt_pk_bf16_f32 v54, v48, v49
	v_pk_mul_f32 v[46:47], v[44:45], v[52:53] op_sel_hi:[1,0]
	v_pk_fma_f32 v[6:7], v[80:81], v[46:47], v[6:7] op_sel_hi:[0,1,1]
	v_pk_fma_f32 v[8:9], v[82:83], v[46:47], v[8:9] op_sel_hi:[0,1,1]
	v_pk_fma_f32 v[10:11], v[84:85], v[46:47], v[10:11] op_sel_hi:[0,1,1]
	v_pk_fma_f32 v[12:13], v[86:87], v[46:47], v[12:13] op_sel_hi:[0,1,1]
	v_pk_fma_f32 v[14:15], v[88:89], v[46:47], v[14:15] op_sel_hi:[0,1,1]
	v_pk_fma_f32 v[16:17], v[90:91], v[46:47], v[16:17] op_sel_hi:[0,1,1]
	v_pk_fma_f32 v[18:19], v[92:93], v[46:47], v[18:19] op_sel_hi:[0,1,1]
	v_pk_fma_f32 v[20:21], v[94:95], v[46:47], v[20:21] op_sel_hi:[0,1,1]
	global_store_dword v154, v54, s[14:15] offset:-4096
	s_waitcnt lgkmcnt(5)
	v_pk_mul_f32 v[38:39], v[6:7], v[56:57] op_sel_hi:[1,0]
	v_pk_mul_f32 v[40:41], v[6:7], v[56:57] op_sel:[0,1] op_sel_hi:[1,1]
	v_pk_fma_f32 v[38:39], v[8:9], v[58:59], v[38:39] op_sel_hi:[1,0,1]
	v_pk_fma_f32 v[40:41], v[8:9], v[58:59], v[40:41] op_sel:[0,1,0] op_sel_hi:[1,1,1]
	s_waitcnt lgkmcnt(4)
	v_pk_fma_f32 v[38:39], v[10:11], v[60:61], v[38:39] op_sel_hi:[1,0,1]
	v_pk_fma_f32 v[40:41], v[10:11], v[60:61], v[40:41] op_sel:[0,1,0] op_sel_hi:[1,1,1]
	v_pk_fma_f32 v[38:39], v[12:13], v[62:63], v[38:39] op_sel_hi:[1,0,1]
	v_pk_fma_f32 v[40:41], v[12:13], v[62:63], v[40:41] op_sel:[0,1,0] op_sel_hi:[1,1,1]
	s_waitcnt lgkmcnt(3)
	v_pk_fma_f32 v[38:39], v[14:15], v[64:65], v[38:39] op_sel_hi:[1,0,1]
	v_pk_fma_f32 v[40:41], v[14:15], v[64:65], v[40:41] op_sel:[0,1,0] op_sel_hi:[1,1,1]
	v_pk_fma_f32 v[38:39], v[16:17], v[66:67], v[38:39] op_sel_hi:[1,0,1]
	v_pk_fma_f32 v[40:41], v[16:17], v[66:67], v[40:41] op_sel:[0,1,0] op_sel_hi:[1,1,1]
	s_waitcnt lgkmcnt(2)
	v_pk_fma_f32 v[38:39], v[18:19], v[68:69], v[38:39] op_sel_hi:[1,0,1]
	v_pk_fma_f32 v[40:41], v[18:19], v[68:69], v[40:41] op_sel:[0,1,0] op_sel_hi:[1,1,1]
	v_pk_fma_f32 v[38:39], v[20:21], v[70:71], v[38:39] op_sel_hi:[1,0,1]
	v_pk_fma_f32 v[40:41], v[20:21], v[70:71], v[40:41] op_sel:[0,1,0] op_sel_hi:[1,1,1]
	s_waitcnt lgkmcnt(0)
	v_mul_f32_e32 v50, v76, v51
	v_add_f32_dpp v38, v38, v38 row_ror:8 row_mask:0xf bank_mask:0x3 bound_ctrl:1
	v_add_f32_dpp v39, v39, v39 row_ror:8 row_mask:0xf bank_mask:0x3 bound_ctrl:1
	v_add_f32_dpp v38, v40, v40 row_ror:8 row_mask:0xf bank_mask:0xc bound_ctrl:1
	v_add_f32_dpp v39, v41, v41 row_ror:8 row_mask:0xf bank_mask:0xc bound_ctrl:1
	ds_read_b128 v[80:83], v2 offset:3328
	v_add_f32_dpp v38, v38, v38 row_half_mirror row_mask:0xf bank_mask:0x5 bound_ctrl:1
	v_add_f32_dpp v38, v39, v39 row_half_mirror row_mask:0xf bank_mask:0xa bound_ctrl:1
	ds_read_b128 v[84:87], v2 offset:3584
	ds_read_b128 v[88:91], v2 offset:3840
	v_add_f32_dpp v38, v38, v38 quad_perm:[1,0,3,2] row_mask:0xf bank_mask:0xf bound_ctrl:1
	ds_read_b128 v[92:95], v2 offset:4096
	ds_read_b64 v[96:97], v3 offset:13312
	v_add_f32_dpp v38, v38, v38 quad_perm:[2,3,0,1] row_mask:0xf bank_mask:0xf bound_ctrl:1
	ds_read_b128 v[100:103], v1 offset:14640
	v_cmp_gt_f32_e32 vcc, 0x2b8cbccc, v50
	v_fmac_f32_dpp v72, -v38, v50 row_newbcast:0 row_mask:0xf bank_mask:0xf bound_ctrl:1
	v_fmac_f32_dpp v73, -v38, v50 row_newbcast:4 row_mask:0xf bank_mask:0xf bound_ctrl:1
	v_pk_mul_f32 v[44:45], v[72:73], v[76:77] op_sel:[0,1] op_sel_hi:[1,1]
	v_pk_mul_f32 v[48:49], v[44:45], v[78:79] op_sel_hi:[1,0]
	v_rcp_f32_e32 v52, v50
	s_add_u32 s14, s14, 0x1000
	s_addc_u32 s15, s15, 0
	v_fmac_f32_dpp v48, v38, v50 row_newbcast:8 row_mask:0xf bank_mask:0xf bound_ctrl:1
	v_fmac_f32_dpp v49, v38, v50 row_newbcast:12 row_mask:0xf bank_mask:0xf bound_ctrl:1
	s_cbranch_vccnz .Lgd2_rare0_2
.Lgd2_back0_2:
	v_cvt_pk_bf16_f32 v54, v48, v49
	v_pk_mul_f32 v[46:47], v[44:45], v[52:53] op_sel_hi:[1,0]
	v_pk_fma_f32 v[6:7], v[56:57], v[46:47], v[6:7] op_sel_hi:[0,1,1]
	v_pk_fma_f32 v[8:9], v[58:59], v[46:47], v[8:9] op_sel_hi:[0,1,1]
	v_pk_fma_f32 v[10:11], v[60:61], v[46:47], v[10:11] op_sel_hi:[0,1,1]
	v_pk_fma_f32 v[12:13], v[62:63], v[46:47], v[12:13] op_sel_hi:[0,1,1]
	v_pk_fma_f32 v[14:15], v[64:65], v[46:47], v[14:15] op_sel_hi:[0,1,1]
	v_pk_fma_f32 v[16:17], v[66:67], v[46:47], v[16:17] op_sel_hi:[0,1,1]
	v_pk_fma_f32 v[18:19], v[68:69], v[46:47], v[18:19] op_sel_hi:[0,1,1]
	v_pk_fma_f32 v[20:21], v[70:71], v[46:47], v[20:21] op_sel_hi:[0,1,1]
	global_store_dword v154, v54, s[14:15] offset:-4096
	s_waitcnt lgkmcnt(5)
	v_pk_mul_f32 v[38:39], v[6:7], v[80:81] op_sel_hi:[1,0]
	v_pk_mul_f32 v[40:41], v[6:7], v[80:81] op_sel:[0,1] op_sel_hi:[1,1]
	v_pk_fma_f32 v[38:39], v[8:9], v[82:83], v[38:39] op_sel_hi:[1,0,1]
	v_pk_fma_f32 v[40:41], v[8:9], v[82:83], v[40:41] op_sel:[0,1,0] op_sel_hi:[1,1,1]
	s_waitcnt lgkmcnt(4)
	v_pk_fma_f32 v[38:39], v[10:11], v[84:85], v[38:39] op_sel_hi:[1,0,1]
	v_pk_fma_f32 v[40:41], v[10:11], v[84:85], v[40:41] op_sel:[0,1,0] op_sel_hi:[1,1,1]
	v_pk_fma_f32 v[38:39], v[12:13], v[86:87], v[38:39] op_sel_hi:[1,0,1]
	v_pk_fma_f32 v[40:41], v[12:13], v[86:87], v[40:41] op_sel:[0,1,0] op_sel_hi:[1,1,1]
	s_waitcnt lgkmcnt(3)
	v_pk_fma_f32 v[38:39], v[14:15], v[88:89], v[38:39] op_sel_hi:[1,0,1]
	v_pk_fma_f32 v[40:41], v[14:15], v[88:89], v[40:41] op_sel:[0,1,0] op_sel_hi:[1,1,1]
	v_pk_fma_f32 v[38:39], v[16:17], v[90:91], v[38:39] op_sel_hi:[1,0,1]
	v_pk_fma_f32 v[40:41], v[16:17], v[90:91], v[40:41] op_sel:[0,1,0] op_sel_hi:[1,1,1]
	s_waitcnt lgkmcnt(2)
	v_pk_fma_f32 v[38:39], v[18:19], v[92:93], v[38:39] op_sel_hi:[1,0,1]
	v_pk_fma_f32 v[40:41], v[18:19], v[92:93], v[40:41] op_sel:[0,1,0] op_sel_hi:[1,1,1]
	v_pk_fma_f32 v[38:39], v[20:21], v[94:95], v[38:39] op_sel_hi:[1,0,1]
	v_pk_fma_f32 v[40:41], v[20:21], v[94:95], v[40:41] op_sel:[0,1,0] op_sel_hi:[1,1,1]
	s_waitcnt lgkmcnt(0)
	v_mul_f32_e32 v51, v100, v50
	v_add_f32_dpp v38, v38, v38 row_ror:8 row_mask:0xf bank_mask:0x3 bound_ctrl:1
	v_add_f32_dpp v39, v39, v39 row_ror:8 row_mask:0xf bank_mask:0x3 bound_ctrl:1
	v_add_f32_dpp v38, v40, v40 row_ror:8 row_mask:0xf bank_mask:0xc bound_ctrl:1
	v_add_f32_dpp v39, v41, v41 row_ror:8 row_mask:0xf bank_mask:0xc bound_ctrl:1
	ds_read_b128 v[56:59], v2 offset:4352
	v_add_f32_dpp v38, v38, v38 row_half_mirror row_mask:0xf bank_mask:0x5 bound_ctrl:1
	v_add_f32_dpp v38, v39, v39 row_half_mirror row_mask:0xf bank_mask:0xa bound_ctrl:1
	ds_read_b128 v[60:63], v2 offset:4608
	ds_read_b128 v[64:67], v2 offset:4864
	v_add_f32_dpp v38, v38, v38 quad_perm:[1,0,3,2] row_mask:0xf bank_mask:0xf bound_ctrl:1
	ds_read_b128 v[68:71], v2 offset:5120
	ds_read_b64 v[72:73], v3 offset:13568
	v_add_f32_dpp v38, v38, v38 quad_perm:[2,3,0,1] row_mask:0xf bank_mask:0xf bound_ctrl:1
	ds_read_b128 v[76:79], v1 offset:14656
	v_cmp_gt_f32_e32 vcc, 0x2b8cbccc, v51
	v_fmac_f32_dpp v96, -v38, v51 row_newbcast:0 row_mask:0xf bank_mask:0xf bound_ctrl:1
	v_fmac_f32_dpp v97, -v38, v51 row_newbcast:4 row_mask:0xf bank_mask:0xf bound_ctrl:1
	v_pk_mul_f32 v[44:45], v[96:97], v[100:101] op_sel:[0,1] op_sel_hi:[1,1]
	v_pk_mul_f32 v[48:49], v[44:45], v[102:103] op_sel_hi:[1,0]
	v_rcp_f32_e32 v52, v51
	s_add_u32 s14, s14, 0x1000
	s_addc_u32 s15, s15, 0
	v_fmac_f32_dpp v48, v38, v51 row_newbcast:8 row_mask:0xf bank_mask:0xf bound_ctrl:1
	v_fmac_f32_dpp v49, v38, v51 row_newbcast:12 row_mask:0xf bank_mask:0xf bound_ctrl:1
	s_cbranch_vccnz .Lgd2_rare0_3
.Lgd2_back0_3:
	v_cvt_pk_bf16_f32 v54, v48, v49
	v_pk_mul_f32 v[46:47], v[44:45], v[52:53] op_sel_hi:[1,0]
	v_pk_fma_f32 v[6:7], v[80:81], v[46:47], v[6:7] op_sel_hi:[0,1,1]
	v_pk_fma_f32 v[8:9], v[82:83], v[46:47], v[8:9] op_sel_hi:[0,1,1]
	v_pk_fma_f32 v[10:11], v[84:85], v[46:47], v[10:11] op_sel_hi:[0,1,1]
	v_pk_fma_f32 v[12:13], v[86:87], v[46:47], v[12:13] op_sel_hi:[0,1,1]
	v_pk_fma_f32 v[14:15], v[88:89], v[46:47], v[14:15] op_sel_hi:[0,1,1]
	v_pk_fma_f32 v[16:17], v[90:91], v[46:47], v[16:17] op_sel_hi:[0,1,1]
	v_pk_fma_f32 v[18:19], v[92:93], v[46:47], v[18:19] op_sel_hi:[0,1,1]
	v_pk_fma_f32 v[20:21], v[94:95], v[46:47], v[20:21] op_sel_hi:[0,1,1]
	global_store_dword v154, v54, s[14:15] offset:-4096
	s_waitcnt lgkmcnt(5)
	v_pk_mul_f32 v[38:39], v[6:7], v[56:57] op_sel_hi:[1,0]
	v_pk_mul_f32 v[40:41], v[6:7], v[56:57] op_sel:[0,1] op_sel_hi:[1,1]
	v_pk_fma_f32 v[38:39], v[8:9], v[58:59], v[38:39] op_sel_hi:[1,0,1]
	v_pk_fma_f32 v[40:41], v[8:9], v[58:59], v[40:41] op_sel:[0,1,0] op_sel_hi:[1,1,1]
	s_waitcnt lgkmcnt(4)
	v_pk_fma_f32 v[38:39], v[10:11], v[60:61], v[38:39] op_sel_hi:[1,0,1]
	v_pk_fma_f32 v[40:41], v[10:11], v[60:61], v[40:41] op_sel:[0,1,0] op_sel_hi:[1,1,1]
	v_pk_fma_f32 v[38:39], v[12:13], v[62:63], v[38:39] op_sel_hi:[1,0,1]
	v_pk_fma_f32 v[40:41], v[12:13], v[62:63], v[40:41] op_sel:[0,1,0] op_sel_hi:[1,1,1]
	s_waitcnt lgkmcnt(3)
	v_pk_fma_f32 v[38:39], v[14:15], v[64:65], v[38:39] op_sel_hi:[1,0,1]
	v_pk_fma_f32 v[40:41], v[14:15], v[64:65], v[40:41] op_sel:[0,1,0] op_sel_hi:[1,1,1]
	v_pk_fma_f32 v[38:39], v[16:17], v[66:67], v[38:39] op_sel_hi:[1,0,1]
	v_pk_fma_f32 v[40:41], v[16:17], v[66:67], v[40:41] op_sel:[0,1,0] op_sel_hi:[1,1,1]
	s_waitcnt lgkmcnt(2)
	v_pk_fma_f32 v[38:39], v[18:19], v[68:69], v[38:39] op_sel_hi:[1,0,1]
	v_pk_fma_f32 v[40:41], v[18:19], v[68:69], v[40:41] op_sel:[0,1,0] op_sel_hi:[1,1,1]
	v_pk_fma_f32 v[38:39], v[20:21], v[70:71], v[38:39] op_sel_hi:[1,0,1]
	v_pk_fma_f32 v[40:41], v[20:21], v[70:71], v[40:41] op_sel:[0,1,0] op_sel_hi:[1,1,1]
	s_waitcnt lgkmcnt(0)
	v_mul_f32_e32 v50, v76, v51
	v_add_f32_dpp v38, v38, v38 row_ror:8 row_mask:0xf bank_mask:0x3 bound_ctrl:1
	v_add_f32_dpp v39, v39, v39 row_ror:8 row_mask:0xf bank_mask:0x3 bound_ctrl:1
	v_add_f32_dpp v38, v40, v40 row_ror:8 row_mask:0xf bank_mask:0xc bound_ctrl:1
	v_add_f32_dpp v39, v41, v41 row_ror:8 row_mask:0xf bank_mask:0xc bound_ctrl:1
	ds_read_b128 v[80:83], v2 offset:5376
	v_add_f32_dpp v38, v38, v38 row_half_mirror row_mask:0xf bank_mask:0x5 bound_ctrl:1
	v_add_f32_dpp v38, v39, v39 row_half_mirror row_mask:0xf bank_mask:0xa bound_ctrl:1
	ds_read_b128 v[84:87], v2 offset:5632
	ds_read_b128 v[88:91], v2 offset:5888
	v_add_f32_dpp v38, v38, v38 quad_perm:[1,0,3,2] row_mask:0xf bank_mask:0xf bound_ctrl:1
	ds_read_b128 v[92:95], v2 offset:6144
	ds_read_b64 v[96:97], v3 offset:13824
	v_add_f32_dpp v38, v38, v38 quad_perm:[2,3,0,1] row_mask:0xf bank_mask:0xf bound_ctrl:1
	ds_read_b128 v[100:103], v1 offset:14672
	v_cmp_gt_f32_e32 vcc, 0x2b8cbccc, v50
	v_fmac_f32_dpp v72, -v38, v50 row_newbcast:0 row_mask:0xf bank_mask:0xf bound_ctrl:1
	v_fmac_f32_dpp v73, -v38, v50 row_newbcast:4 row_mask:0xf bank_mask:0xf bound_ctrl:1
	v_pk_mul_f32 v[44:45], v[72:73], v[76:77] op_sel:[0,1] op_sel_hi:[1,1]
	v_pk_mul_f32 v[48:49], v[44:45], v[78:79] op_sel_hi:[1,0]
	v_rcp_f32_e32 v52, v50
	s_add_u32 s14, s14, 0x1000
	s_addc_u32 s15, s15, 0
	v_fmac_f32_dpp v48, v38, v50 row_newbcast:8 row_mask:0xf bank_mask:0xf bound_ctrl:1
	v_fmac_f32_dpp v49, v38, v50 row_newbcast:12 row_mask:0xf bank_mask:0xf bound_ctrl:1
	s_cbranch_vccnz .Lgd2_rare0_4
.Lgd2_back0_4:
	v_cvt_pk_bf16_f32 v54, v48, v49
	v_pk_mul_f32 v[46:47], v[44:45], v[52:53] op_sel_hi:[1,0]
	v_pk_fma_f32 v[6:7], v[56:57], v[46:47], v[6:7] op_sel_hi:[0,1,1]
	v_pk_fma_f32 v[8:9], v[58:59], v[46:47], v[8:9] op_sel_hi:[0,1,1]
	v_pk_fma_f32 v[10:11], v[60:61], v[46:47], v[10:11] op_sel_hi:[0,1,1]
	v_pk_fma_f32 v[12:13], v[62:63], v[46:47], v[12:13] op_sel_hi:[0,1,1]
	v_pk_fma_f32 v[14:15], v[64:65], v[46:47], v[14:15] op_sel_hi:[0,1,1]
	v_pk_fma_f32 v[16:17], v[66:67], v[46:47], v[16:17] op_sel_hi:[0,1,1]
	v_pk_fma_f32 v[18:19], v[68:69], v[46:47], v[18:19] op_sel_hi:[0,1,1]
	v_pk_fma_f32 v[20:21], v[70:71], v[46:47], v[20:21] op_sel_hi:[0,1,1]
	global_store_dword v154, v54, s[14:15] offset:-4096
	s_waitcnt lgkmcnt(5)
	v_pk_mul_f32 v[38:39], v[6:7], v[80:81] op_sel_hi:[1,0]
	v_pk_mul_f32 v[40:41], v[6:7], v[80:81] op_sel:[0,1] op_sel_hi:[1,1]
	v_pk_fma_f32 v[38:39], v[8:9], v[82:83], v[38:39] op_sel_hi:[1,0,1]
	v_pk_fma_f32 v[40:41], v[8:9], v[82:83], v[40:41] op_sel:[0,1,0] op_sel_hi:[1,1,1]
	s_waitcnt lgkmcnt(4)
	v_pk_fma_f32 v[38:39], v[10:11], v[84:85], v[38:39] op_sel_hi:[1,0,1]
	v_pk_fma_f32 v[40:41], v[10:11], v[84:85], v[40:41] op_sel:[0,1,0] op_sel_hi:[1,1,1]
	v_pk_fma_f32 v[38:39], v[12:13], v[86:87], v[38:39] op_sel_hi:[1,0,1]
	v_pk_fma_f32 v[40:41], v[12:13], v[86:87], v[40:41] op_sel:[0,1,0] op_sel_hi:[1,1,1]
	s_waitcnt lgkmcnt(3)
	v_pk_fma_f32 v[38:39], v[14:15], v[88:89], v[38:39] op_sel_hi:[1,0,1]
	v_pk_fma_f32 v[40:41], v[14:15], v[88:89], v[40:41] op_sel:[0,1,0] op_sel_hi:[1,1,1]
	v_pk_fma_f32 v[38:39], v[16:17], v[90:91], v[38:39] op_sel_hi:[1,0,1]
	v_pk_fma_f32 v[40:41], v[16:17], v[90:91], v[40:41] op_sel:[0,1,0] op_sel_hi:[1,1,1]
	s_waitcnt lgkmcnt(2)
	v_pk_fma_f32 v[38:39], v[18:19], v[92:93], v[38:39] op_sel_hi:[1,0,1]
	v_pk_fma_f32 v[40:41], v[18:19], v[92:93], v[40:41] op_sel:[0,1,0] op_sel_hi:[1,1,1]
	v_pk_fma_f32 v[38:39], v[20:21], v[94:95], v[38:39] op_sel_hi:[1,0,1]
	v_pk_fma_f32 v[40:41], v[20:21], v[94:95], v[40:41] op_sel:[0,1,0] op_sel_hi:[1,1,1]
	s_waitcnt lgkmcnt(0)
	v_mul_f32_e32 v51, v100, v50
	v_add_f32_dpp v38, v38, v38 row_ror:8 row_mask:0xf bank_mask:0x3 bound_ctrl:1
	v_add_f32_dpp v39, v39, v39 row_ror:8 row_mask:0xf bank_mask:0x3 bound_ctrl:1
	v_add_f32_dpp v38, v40, v40 row_ror:8 row_mask:0xf bank_mask:0xc bound_ctrl:1
	v_add_f32_dpp v39, v41, v41 row_ror:8 row_mask:0xf bank_mask:0xc bound_ctrl:1
	ds_read_b128 v[56:59], v2 offset:6400
	v_add_f32_dpp v38, v38, v38 row_half_mirror row_mask:0xf bank_mask:0x5 bound_ctrl:1
	v_add_f32_dpp v38, v39, v39 row_half_mirror row_mask:0xf bank_mask:0xa bound_ctrl:1
	ds_read_b128 v[60:63], v2 offset:6656
	ds_read_b128 v[64:67], v2 offset:6912
	v_add_f32_dpp v38, v38, v38 quad_perm:[1,0,3,2] row_mask:0xf bank_mask:0xf bound_ctrl:1
	ds_read_b128 v[68:71], v2 offset:7168
	ds_read_b64 v[72:73], v3 offset:14080
	v_add_f32_dpp v38, v38, v38 quad_perm:[2,3,0,1] row_mask:0xf bank_mask:0xf bound_ctrl:1
	ds_read_b128 v[76:79], v1 offset:14688
	v_cmp_gt_f32_e32 vcc, 0x2b8cbccc, v51
	v_fmac_f32_dpp v96, -v38, v51 row_newbcast:0 row_mask:0xf bank_mask:0xf bound_ctrl:1
	v_fmac_f32_dpp v97, -v38, v51 row_newbcast:4 row_mask:0xf bank_mask:0xf bound_ctrl:1
	v_pk_mul_f32 v[44:45], v[96:97], v[100:101] op_sel:[0,1] op_sel_hi:[1,1]
	v_pk_mul_f32 v[48:49], v[44:45], v[102:103] op_sel_hi:[1,0]
	v_rcp_f32_e32 v52, v51
	s_add_u32 s14, s14, 0x1000
	s_addc_u32 s15, s15, 0
	v_fmac_f32_dpp v48, v38, v51 row_newbcast:8 row_mask:0xf bank_mask:0xf bound_ctrl:1
	v_fmac_f32_dpp v49, v38, v51 row_newbcast:12 row_mask:0xf bank_mask:0xf bound_ctrl:1
	s_cbranch_vccnz .Lgd2_rare0_5
.Lgd2_back0_5:
	v_cvt_pk_bf16_f32 v54, v48, v49
	v_pk_mul_f32 v[46:47], v[44:45], v[52:53] op_sel_hi:[1,0]
	v_pk_fma_f32 v[6:7], v[80:81], v[46:47], v[6:7] op_sel_hi:[0,1,1]
	v_pk_fma_f32 v[8:9], v[82:83], v[46:47], v[8:9] op_sel_hi:[0,1,1]
	v_pk_fma_f32 v[10:11], v[84:85], v[46:47], v[10:11] op_sel_hi:[0,1,1]
	v_pk_fma_f32 v[12:13], v[86:87], v[46:47], v[12:13] op_sel_hi:[0,1,1]
	v_pk_fma_f32 v[14:15], v[88:89], v[46:47], v[14:15] op_sel_hi:[0,1,1]
	v_pk_fma_f32 v[16:17], v[90:91], v[46:47], v[16:17] op_sel_hi:[0,1,1]
	v_pk_fma_f32 v[18:19], v[92:93], v[46:47], v[18:19] op_sel_hi:[0,1,1]
	v_pk_fma_f32 v[20:21], v[94:95], v[46:47], v[20:21] op_sel_hi:[0,1,1]
	global_store_dword v154, v54, s[14:15] offset:-4096
	s_waitcnt lgkmcnt(5)
	v_pk_mul_f32 v[38:39], v[6:7], v[56:57] op_sel_hi:[1,0]
	v_pk_mul_f32 v[40:41], v[6:7], v[56:57] op_sel:[0,1] op_sel_hi:[1,1]
	v_pk_fma_f32 v[38:39], v[8:9], v[58:59], v[38:39] op_sel_hi:[1,0,1]
	v_pk_fma_f32 v[40:41], v[8:9], v[58:59], v[40:41] op_sel:[0,1,0] op_sel_hi:[1,1,1]
	s_waitcnt lgkmcnt(4)
	v_pk_fma_f32 v[38:39], v[10:11], v[60:61], v[38:39] op_sel_hi:[1,0,1]
	v_pk_fma_f32 v[40:41], v[10:11], v[60:61], v[40:41] op_sel:[0,1,0] op_sel_hi:[1,1,1]
	v_pk_fma_f32 v[38:39], v[12:13], v[62:63], v[38:39] op_sel_hi:[1,0,1]
	v_pk_fma_f32 v[40:41], v[12:13], v[62:63], v[40:41] op_sel:[0,1,0] op_sel_hi:[1,1,1]
	s_waitcnt lgkmcnt(3)
	v_pk_fma_f32 v[38:39], v[14:15], v[64:65], v[38:39] op_sel_hi:[1,0,1]
	v_pk_fma_f32 v[40:41], v[14:15], v[64:65], v[40:41] op_sel:[0,1,0] op_sel_hi:[1,1,1]
	v_pk_fma_f32 v[38:39], v[16:17], v[66:67], v[38:39] op_sel_hi:[1,0,1]
	v_pk_fma_f32 v[40:41], v[16:17], v[66:67], v[40:41] op_sel:[0,1,0] op_sel_hi:[1,1,1]
	s_waitcnt lgkmcnt(2)
	v_pk_fma_f32 v[38:39], v[18:19], v[68:69], v[38:39] op_sel_hi:[1,0,1]
	v_pk_fma_f32 v[40:41], v[18:19], v[68:69], v[40:41] op_sel:[0,1,0] op_sel_hi:[1,1,1]
	v_pk_fma_f32 v[38:39], v[20:21], v[70:71], v[38:39] op_sel_hi:[1,0,1]
	v_pk_fma_f32 v[40:41], v[20:21], v[70:71], v[40:41] op_sel:[0,1,0] op_sel_hi:[1,1,1]
	s_waitcnt lgkmcnt(0)
	v_mul_f32_e32 v50, v76, v51
	v_add_f32_dpp v38, v38, v38 row_ror:8 row_mask:0xf bank_mask:0x3 bound_ctrl:1
	v_add_f32_dpp v39, v39, v39 row_ror:8 row_mask:0xf bank_mask:0x3 bound_ctrl:1
	v_add_f32_dpp v38, v40, v40 row_ror:8 row_mask:0xf bank_mask:0xc bound_ctrl:1
	v_add_f32_dpp v39, v41, v41 row_ror:8 row_mask:0xf bank_mask:0xc bound_ctrl:1
	ds_read_b128 v[80:83], v2 offset:7424
	v_add_f32_dpp v38, v38, v38 row_half_mirror row_mask:0xf bank_mask:0x5 bound_ctrl:1
	v_add_f32_dpp v38, v39, v39 row_half_mirror row_mask:0xf bank_mask:0xa bound_ctrl:1
	ds_read_b128 v[84:87], v2 offset:7680
	ds_read_b128 v[88:91], v2 offset:7936
	v_add_f32_dpp v38, v38, v38 quad_perm:[1,0,3,2] row_mask:0xf bank_mask:0xf bound_ctrl:1
	ds_read_b128 v[92:95], v2 offset:8192
	ds_read_b64 v[96:97], v3 offset:14336
	v_add_f32_dpp v38, v38, v38 quad_perm:[2,3,0,1] row_mask:0xf bank_mask:0xf bound_ctrl:1
	ds_read_b128 v[100:103], v1 offset:14704
	v_cmp_gt_f32_e32 vcc, 0x2b8cbccc, v50
	v_fmac_f32_dpp v72, -v38, v50 row_newbcast:0 row_mask:0xf bank_mask:0xf bound_ctrl:1
	v_fmac_f32_dpp v73, -v38, v50 row_newbcast:4 row_mask:0xf bank_mask:0xf bound_ctrl:1
	v_pk_mul_f32 v[44:45], v[72:73], v[76:77] op_sel:[0,1] op_sel_hi:[1,1]
	v_pk_mul_f32 v[48:49], v[44:45], v[78:79] op_sel_hi:[1,0]
	v_rcp_f32_e32 v52, v50
	s_add_u32 s14, s14, 0x1000
	s_addc_u32 s15, s15, 0
	v_fmac_f32_dpp v48, v38, v50 row_newbcast:8 row_mask:0xf bank_mask:0xf bound_ctrl:1
	v_fmac_f32_dpp v49, v38, v50 row_newbcast:12 row_mask:0xf bank_mask:0xf bound_ctrl:1
	s_cbranch_vccnz .Lgd2_rare0_6
.Lgd2_back0_6:
	v_cvt_pk_bf16_f32 v54, v48, v49
	v_pk_mul_f32 v[46:47], v[44:45], v[52:53] op_sel_hi:[1,0]
	v_pk_fma_f32 v[6:7], v[56:57], v[46:47], v[6:7] op_sel_hi:[0,1,1]
	v_pk_fma_f32 v[8:9], v[58:59], v[46:47], v[8:9] op_sel_hi:[0,1,1]
	v_pk_fma_f32 v[10:11], v[60:61], v[46:47], v[10:11] op_sel_hi:[0,1,1]
	v_pk_fma_f32 v[12:13], v[62:63], v[46:47], v[12:13] op_sel_hi:[0,1,1]
	v_pk_fma_f32 v[14:15], v[64:65], v[46:47], v[14:15] op_sel_hi:[0,1,1]
	v_pk_fma_f32 v[16:17], v[66:67], v[46:47], v[16:17] op_sel_hi:[0,1,1]
	v_pk_fma_f32 v[18:19], v[68:69], v[46:47], v[18:19] op_sel_hi:[0,1,1]
	v_pk_fma_f32 v[20:21], v[70:71], v[46:47], v[20:21] op_sel_hi:[0,1,1]
	global_store_dword v154, v54, s[14:15] offset:-4096
	s_waitcnt lgkmcnt(5)
	v_pk_mul_f32 v[38:39], v[6:7], v[80:81] op_sel_hi:[1,0]
	v_pk_mul_f32 v[40:41], v[6:7], v[80:81] op_sel:[0,1] op_sel_hi:[1,1]
	v_pk_fma_f32 v[38:39], v[8:9], v[82:83], v[38:39] op_sel_hi:[1,0,1]
	v_pk_fma_f32 v[40:41], v[8:9], v[82:83], v[40:41] op_sel:[0,1,0] op_sel_hi:[1,1,1]
	s_waitcnt lgkmcnt(4)
	v_pk_fma_f32 v[38:39], v[10:11], v[84:85], v[38:39] op_sel_hi:[1,0,1]
	v_pk_fma_f32 v[40:41], v[10:11], v[84:85], v[40:41] op_sel:[0,1,0] op_sel_hi:[1,1,1]
	v_pk_fma_f32 v[38:39], v[12:13], v[86:87], v[38:39] op_sel_hi:[1,0,1]
	v_pk_fma_f32 v[40:41], v[12:13], v[86:87], v[40:41] op_sel:[0,1,0] op_sel_hi:[1,1,1]
	s_waitcnt lgkmcnt(3)
	v_pk_fma_f32 v[38:39], v[14:15], v[88:89], v[38:39] op_sel_hi:[1,0,1]
	v_pk_fma_f32 v[40:41], v[14:15], v[88:89], v[40:41] op_sel:[0,1,0] op_sel_hi:[1,1,1]
	v_pk_fma_f32 v[38:39], v[16:17], v[90:91], v[38:39] op_sel_hi:[1,0,1]
	v_pk_fma_f32 v[40:41], v[16:17], v[90:91], v[40:41] op_sel:[0,1,0] op_sel_hi:[1,1,1]
	s_waitcnt lgkmcnt(2)
	v_pk_fma_f32 v[38:39], v[18:19], v[92:93], v[38:39] op_sel_hi:[1,0,1]
	v_pk_fma_f32 v[40:41], v[18:19], v[92:93], v[40:41] op_sel:[0,1,0] op_sel_hi:[1,1,1]
	v_pk_fma_f32 v[38:39], v[20:21], v[94:95], v[38:39] op_sel_hi:[1,0,1]
	v_pk_fma_f32 v[40:41], v[20:21], v[94:95], v[40:41] op_sel:[0,1,0] op_sel_hi:[1,1,1]
	s_waitcnt lgkmcnt(0)
	v_mul_f32_e32 v51, v100, v50
	v_add_f32_dpp v38, v38, v38 row_ror:8 row_mask:0xf bank_mask:0x3 bound_ctrl:1
	v_add_f32_dpp v39, v39, v39 row_ror:8 row_mask:0xf bank_mask:0x3 bound_ctrl:1
	v_add_f32_dpp v38, v40, v40 row_ror:8 row_mask:0xf bank_mask:0xc bound_ctrl:1
	v_add_f32_dpp v39, v41, v41 row_ror:8 row_mask:0xf bank_mask:0xc bound_ctrl:1
	ds_read_b128 v[56:59], v2 offset:16640
	v_add_f32_dpp v38, v38, v38 row_half_mirror row_mask:0xf bank_mask:0x5 bound_ctrl:1
	v_add_f32_dpp v38, v39, v39 row_half_mirror row_mask:0xf bank_mask:0xa bound_ctrl:1
	ds_read_b128 v[60:63], v2 offset:16896
	ds_read_b128 v[64:67], v2 offset:17152
	v_add_f32_dpp v38, v38, v38 quad_perm:[1,0,3,2] row_mask:0xf bank_mask:0xf bound_ctrl:1
	ds_read_b128 v[68:71], v2 offset:17408
	ds_read_b64 v[72:73], v3 offset:28928
	v_add_f32_dpp v38, v38, v38 quad_perm:[2,3,0,1] row_mask:0xf bank_mask:0xf bound_ctrl:1
	ds_read_b128 v[76:79], v1 offset:30976
	v_cmp_gt_f32_e32 vcc, 0x2b8cbccc, v51
	v_fmac_f32_dpp v96, -v38, v51 row_newbcast:0 row_mask:0xf bank_mask:0xf bound_ctrl:1
	v_fmac_f32_dpp v97, -v38, v51 row_newbcast:4 row_mask:0xf bank_mask:0xf bound_ctrl:1
	v_pk_mul_f32 v[44:45], v[96:97], v[100:101] op_sel:[0,1] op_sel_hi:[1,1]
	v_pk_mul_f32 v[48:49], v[44:45], v[102:103] op_sel_hi:[1,0]
	v_rcp_f32_e32 v52, v51
	s_add_u32 s14, s14, 0x1000
	s_addc_u32 s15, s15, 0
	v_fmac_f32_dpp v48, v38, v51 row_newbcast:8 row_mask:0xf bank_mask:0xf bound_ctrl:1
	v_fmac_f32_dpp v49, v38, v51 row_newbcast:12 row_mask:0xf bank_mask:0xf bound_ctrl:1
	s_cbranch_vccnz .Lgd2_rare0_7
.Lgd2_back0_7:
	v_cvt_pk_bf16_f32 v54, v48, v49
	v_pk_mul_f32 v[46:47], v[44:45], v[52:53] op_sel_hi:[1,0]
	v_pk_fma_f32 v[6:7], v[80:81], v[46:47], v[6:7] op_sel_hi:[0,1,1]
	v_pk_fma_f32 v[8:9], v[82:83], v[46:47], v[8:9] op_sel_hi:[0,1,1]
	v_pk_fma_f32 v[10:11], v[84:85], v[46:47], v[10:11] op_sel_hi:[0,1,1]
	v_pk_fma_f32 v[12:13], v[86:87], v[46:47], v[12:13] op_sel_hi:[0,1,1]
	v_pk_fma_f32 v[14:15], v[88:89], v[46:47], v[14:15] op_sel_hi:[0,1,1]
	v_pk_fma_f32 v[16:17], v[90:91], v[46:47], v[16:17] op_sel_hi:[0,1,1]
	v_pk_fma_f32 v[18:19], v[92:93], v[46:47], v[18:19] op_sel_hi:[0,1,1]
	v_pk_fma_f32 v[20:21], v[94:95], v[46:47], v[20:21] op_sel_hi:[0,1,1]
	global_store_dword v154, v54, s[14:15] offset:-4096
	s_waitcnt vmcnt(8)
	v_lshlrev_b32_e32 v116, 16, v108
	v_lshlrev_b32_e32 v117, 16, v109
	v_and_b32_e32 v118, s17, v108
	v_and_b32_e32 v119, s17, v109
	v_lshlrev_b32_e32 v120, 16, v110
	v_and_b32_e32 v121, s17, v110
	v_lshlrev_b32_e32 v122, 16, v111
	v_and_b32_e32 v123, s17, v111
	v_lshlrev_b32_e32 v124, 16, v112
	v_and_b32_e32 v125, s17, v112
	ds_write_b128 v32, v[116:119] offset:33024
	ds_write_b64 v33, v[120:121] offset:33024
	ds_write_b64 v34, v[122:123] offset:33024
	ds_write_b64 v34, v[124:125] offset:33152
	ds_write_b32 v35, v113 offset:33024
	s_add_i32 s16, s16, 8
	s_waitcnt lgkmcnt(0)
	s_barrier
	s_cmpk_lt_u32 s16, 0x800
	s_cbranch_scc0 .Lgd2_done
	global_load_dword v108, v36, s[8:9]
	global_load_dword v109, v36, s[8:9] offset:-2048
	global_load_dword v111, v104, s[8:9] offset:2048
	global_load_dword v110, v37, s[10:11]
	global_load_dword v112, v105, s[10:11]
	global_load_dword v113, v106, s[12:13]
	s_add_u32 s8, s8, 0xc000
	s_addc_u32 s9, s9, 0
	s_add_u32 s10, s10, 0x20000
	s_addc_u32 s11, s11, 0
	s_add_u32 s12, s12, 0x400
	s_addc_u32 s13, s13, 0
	s_waitcnt lgkmcnt(5)
	v_pk_mul_f32 v[38:39], v[6:7], v[56:57] op_sel_hi:[1,0]
	v_pk_mul_f32 v[40:41], v[6:7], v[56:57] op_sel:[0,1] op_sel_hi:[1,1]
	v_pk_fma_f32 v[38:39], v[8:9], v[58:59], v[38:39] op_sel_hi:[1,0,1]
	v_pk_fma_f32 v[40:41], v[8:9], v[58:59], v[40:41] op_sel:[0,1,0] op_sel_hi:[1,1,1]
	s_waitcnt lgkmcnt(4)
	v_pk_fma_f32 v[38:39], v[10:11], v[60:61], v[38:39] op_sel_hi:[1,0,1]
	v_pk_fma_f32 v[40:41], v[10:11], v[60:61], v[40:41] op_sel:[0,1,0] op_sel_hi:[1,1,1]
	v_pk_fma_f32 v[38:39], v[12:13], v[62:63], v[38:39] op_sel_hi:[1,0,1]
	v_pk_fma_f32 v[40:41], v[12:13], v[62:63], v[40:41] op_sel:[0,1,0] op_sel_hi:[1,1,1]
	s_waitcnt lgkmcnt(3)
	v_pk_fma_f32 v[38:39], v[14:15], v[64:65], v[38:39] op_sel_hi:[1,0,1]
	v_pk_fma_f32 v[40:41], v[14:15], v[64:65], v[40:41] op_sel:[0,1,0] op_sel_hi:[1,1,1]
	v_pk_fma_f32 v[38:39], v[16:17], v[66:67], v[38:39] op_sel_hi:[1,0,1]
	v_pk_fma_f32 v[40:41], v[16:17], v[66:67], v[40:41] op_sel:[0,1,0] op_sel_hi:[1,1,1]
	s_waitcnt lgkmcnt(2)
	v_pk_fma_f32 v[38:39], v[18:19], v[68:69], v[38:39] op_sel_hi:[1,0,1]
	v_pk_fma_f32 v[40:41], v[18:19], v[68:69], v[40:41] op_sel:[0,1,0] op_sel_hi:[1,1,1]
	v_pk_fma_f32 v[38:39], v[20:21], v[70:71], v[38:39] op_sel_hi:[1,0,1]
	v_pk_fma_f32 v[40:41], v[20:21], v[70:71], v[40:41] op_sel:[0,1,0] op_sel_hi:[1,1,1]
	s_waitcnt lgkmcnt(0)
	v_mul_f32_e32 v50, v76, v51
	v_add_f32_dpp v38, v38, v38 row_ror:8 row_mask:0xf bank_mask:0x3 bound_ctrl:1
	v_add_f32_dpp v39, v39, v39 row_ror:8 row_mask:0xf bank_mask:0x3 bound_ctrl:1
	v_add_f32_dpp v38, v40, v40 row_ror:8 row_mask:0xf bank_mask:0xc bound_ctrl:1
	v_add_f32_dpp v39, v41, v41 row_ror:8 row_mask:0xf bank_mask:0xc bound_ctrl:1
	ds_read_b128 v[80:83], v2 offset:17664
	v_add_f32_dpp v38, v38, v38 row_half_mirror row_mask:0xf bank_mask:0x5 bound_ctrl:1
	v_add_f32_dpp v38, v39, v39 row_half_mirror row_mask:0xf bank_mask:0xa bound_ctrl:1
	ds_read_b128 v[84:87], v2 offset:17920
	ds_read_b128 v[88:91], v2 offset:18176
	v_add_f32_dpp v38, v38, v38 quad_perm:[1,0,3,2] row_mask:0xf bank_mask:0xf bound_ctrl:1
	ds_read_b128 v[92:95], v2 offset:18432
	ds_read_b64 v[96:97], v3 offset:29184
	v_add_f32_dpp v38, v38, v38 quad_perm:[2,3,0,1] row_mask:0xf bank_mask:0xf bound_ctrl:1
	ds_read_b128 v[100:103], v1 offset:30992
	v_cmp_gt_f32_e32 vcc, 0x2b8cbccc, v50
	v_fmac_f32_dpp v72, -v38, v50 row_newbcast:0 row_mask:0xf bank_mask:0xf bound_ctrl:1
	v_fmac_f32_dpp v73, -v38, v50 row_newbcast:4 row_mask:0xf bank_mask:0xf bound_ctrl:1
	v_pk_mul_f32 v[44:45], v[72:73], v[76:77] op_sel:[0,1] op_sel_hi:[1,1]
	v_pk_mul_f32 v[48:49], v[44:45], v[78:79] op_sel_hi:[1,0]
	v_rcp_f32_e32 v52, v50
	s_add_u32 s14, s14, 0x1000
	s_addc_u32 s15, s15, 0
	v_fmac_f32_dpp v48, v38, v50 row_newbcast:8 row_mask:0xf bank_mask:0xf bound_ctrl:1
	v_fmac_f32_dpp v49, v38, v50 row_newbcast:12 row_mask:0xf bank_mask:0xf bound_ctrl:1
	s_cbranch_vccnz .Lgd2_rare1_0
.Lgd2_back1_0:
	v_cvt_pk_bf16_f32 v54, v48, v49
	v_pk_mul_f32 v[46:47], v[44:45], v[52:53] op_sel_hi:[1,0]
	v_pk_fma_f32 v[6:7], v[56:57], v[46:47], v[6:7] op_sel_hi:[0,1,1]
	v_pk_fma_f32 v[8:9], v[58:59], v[46:47], v[8:9] op_sel_hi:[0,1,1]
	v_pk_fma_f32 v[10:11], v[60:61], v[46:47], v[10:11] op_sel_hi:[0,1,1]
	v_pk_fma_f32 v[12:13], v[62:63], v[46:47], v[12:13] op_sel_hi:[0,1,1]
	v_pk_fma_f32 v[14:15], v[64:65], v[46:47], v[14:15] op_sel_hi:[0,1,1]
	v_pk_fma_f32 v[16:17], v[66:67], v[46:47], v[16:17] op_sel_hi:[0,1,1]
	v_pk_fma_f32 v[18:19], v[68:69], v[46:47], v[18:19] op_sel_hi:[0,1,1]
	v_pk_fma_f32 v[20:21], v[70:71], v[46:47], v[20:21] op_sel_hi:[0,1,1]
	global_store_dword v154, v54, s[14:15] offset:-4096
	s_waitcnt lgkmcnt(5)
	v_pk_mul_f32 v[38:39], v[6:7], v[80:81] op_sel_hi:[1,0]
	v_pk_mul_f32 v[40:41], v[6:7], v[80:81] op_sel:[0,1] op_sel_hi:[1,1]
	v_pk_fma_f32 v[38:39], v[8:9], v[82:83], v[38:39] op_sel_hi:[1,0,1]
	v_pk_fma_f32 v[40:41], v[8:9], v[82:83], v[40:41] op_sel:[0,1,0] op_sel_hi:[1,1,1]
	s_waitcnt lgkmcnt(4)
	v_pk_fma_f32 v[38:39], v[10:11], v[84:85], v[38:39] op_sel_hi:[1,0,1]
	v_pk_fma_f32 v[40:41], v[10:11], v[84:85], v[40:41] op_sel:[0,1,0] op_sel_hi:[1,1,1]
	v_pk_fma_f32 v[38:39], v[12:13], v[86:87], v[38:39] op_sel_hi:[1,0,1]
	v_pk_fma_f32 v[40:41], v[12:13], v[86:87], v[40:41] op_sel:[0,1,0] op_sel_hi:[1,1,1]
	s_waitcnt lgkmcnt(3)
	v_pk_fma_f32 v[38:39], v[14:15], v[88:89], v[38:39] op_sel_hi:[1,0,1]
	v_pk_fma_f32 v[40:41], v[14:15], v[88:89], v[40:41] op_sel:[0,1,0] op_sel_hi:[1,1,1]
	v_pk_fma_f32 v[38:39], v[16:17], v[90:91], v[38:39] op_sel_hi:[1,0,1]
	v_pk_fma_f32 v[40:41], v[16:17], v[90:91], v[40:41] op_sel:[0,1,0] op_sel_hi:[1,1,1]
	s_waitcnt lgkmcnt(2)
	v_pk_fma_f32 v[38:39], v[18:19], v[92:93], v[38:39] op_sel_hi:[1,0,1]
	v_pk_fma_f32 v[40:41], v[18:19], v[92:93], v[40:41] op_sel:[0,1,0] op_sel_hi:[1,1,1]
	v_pk_fma_f32 v[38:39], v[20:21], v[94:95], v[38:39] op_sel_hi:[1,0,1]
	v_pk_fma_f32 v[40:41], v[20:21], v[94:95], v[40:41] op_sel:[0,1,0] op_sel_hi:[1,1,1]
	s_waitcnt lgkmcnt(0)
	v_mul_f32_e32 v51, v100, v50
	v_add_f32_dpp v38, v38, v38 row_ror:8 row_mask:0xf bank_mask:0x3 bound_ctrl:1
	v_add_f32_dpp v39, v39, v39 row_ror:8 row_mask:0xf bank_mask:0x3 bound_ctrl:1
	v_add_f32_dpp v38, v40, v40 row_ror:8 row_mask:0xf bank_mask:0xc bound_ctrl:1
	v_add_f32_dpp v39, v41, v41 row_ror:8 row_mask:0xf bank_mask:0xc bound_ctrl:1
	ds_read_b128 v[56:59], v2 offset:18688
	v_add_f32_dpp v38, v38, v38 row_half_mirror row_mask:0xf bank_mask:0x5 bound_ctrl:1
	v_add_f32_dpp v38, v39, v39 row_half_mirror row_mask:0xf bank_mask:0xa bound_ctrl:1
	ds_read_b128 v[60:63], v2 offset:18944
	ds_read_b128 v[64:67], v2 offset:19200
	v_add_f32_dpp v38, v38, v38 quad_perm:[1,0,3,2] row_mask:0xf bank_mask:0xf bound_ctrl:1
	ds_read_b128 v[68:71], v2 offset:19456
	ds_read_b64 v[72:73], v3 offset:29440
	v_add_f32_dpp v38, v38, v38 quad_perm:[2,3,0,1] row_mask:0xf bank_mask:0xf bound_ctrl:1
	ds_read_b128 v[76:79], v1 offset:31008
	v_cmp_gt_f32_e32 vcc, 0x2b8cbccc, v51
	v_fmac_f32_dpp v96, -v38, v51 row_newbcast:0 row_mask:0xf bank_mask:0xf bound_ctrl:1
	v_fmac_f32_dpp v97, -v38, v51 row_newbcast:4 row_mask:0xf bank_mask:0xf bound_ctrl:1
	v_pk_mul_f32 v[44:45], v[96:97], v[100:101] op_sel:[0,1] op_sel_hi:[1,1]
	v_pk_mul_f32 v[48:49], v[44:45], v[102:103] op_sel_hi:[1,0]
	v_rcp_f32_e32 v52, v51
	s_add_u32 s14, s14, 0x1000
	s_addc_u32 s15, s15, 0
	v_fmac_f32_dpp v48, v38, v51 row_newbcast:8 row_mask:0xf bank_mask:0xf bound_ctrl:1
	v_fmac_f32_dpp v49, v38, v51 row_newbcast:12 row_mask:0xf bank_mask:0xf bound_ctrl:1
	s_cbranch_vccnz .Lgd2_rare1_1
.Lgd2_back1_1:
	v_cvt_pk_bf16_f32 v54, v48, v49
	v_pk_mul_f32 v[46:47], v[44:45], v[52:53] op_sel_hi:[1,0]
	v_pk_fma_f32 v[6:7], v[80:81], v[46:47], v[6:7] op_sel_hi:[0,1,1]
	v_pk_fma_f32 v[8:9], v[82:83], v[46:47], v[8:9] op_sel_hi:[0,1,1]
	v_pk_fma_f32 v[10:11], v[84:85], v[46:47], v[10:11] op_sel_hi:[0,1,1]
	v_pk_fma_f32 v[12:13], v[86:87], v[46:47], v[12:13] op_sel_hi:[0,1,1]
	v_pk_fma_f32 v[14:15], v[88:89], v[46:47], v[14:15] op_sel_hi:[0,1,1]
	v_pk_fma_f32 v[16:17], v[90:91], v[46:47], v[16:17] op_sel_hi:[0,1,1]
	v_pk_fma_f32 v[18:19], v[92:93], v[46:47], v[18:19] op_sel_hi:[0,1,1]
	v_pk_fma_f32 v[20:21], v[94:95], v[46:47], v[20:21] op_sel_hi:[0,1,1]
	global_store_dword v154, v54, s[14:15] offset:-4096
	s_waitcnt lgkmcnt(5)
	v_pk_mul_f32 v[38:39], v[6:7], v[56:57] op_sel_hi:[1,0]
	v_pk_mul_f32 v[40:41], v[6:7], v[56:57] op_sel:[0,1] op_sel_hi:[1,1]
	v_pk_fma_f32 v[38:39], v[8:9], v[58:59], v[38:39] op_sel_hi:[1,0,1]
	v_pk_fma_f32 v[40:41], v[8:9], v[58:59], v[40:41] op_sel:[0,1,0] op_sel_hi:[1,1,1]
	s_waitcnt lgkmcnt(4)
	v_pk_fma_f32 v[38:39], v[10:11], v[60:61], v[38:39] op_sel_hi:[1,0,1]
	v_pk_fma_f32 v[40:41], v[10:11], v[60:61], v[40:41] op_sel:[0,1,0] op_sel_hi:[1,1,1]
	v_pk_fma_f32 v[38:39], v[12:13], v[62:63], v[38:39] op_sel_hi:[1,0,1]
	v_pk_fma_f32 v[40:41], v[12:13], v[62:63], v[40:41] op_sel:[0,1,0] op_sel_hi:[1,1,1]
	s_waitcnt lgkmcnt(3)
	v_pk_fma_f32 v[38:39], v[14:15], v[64:65], v[38:39] op_sel_hi:[1,0,1]
	v_pk_fma_f32 v[40:41], v[14:15], v[64:65], v[40:41] op_sel:[0,1,0] op_sel_hi:[1,1,1]
	v_pk_fma_f32 v[38:39], v[16:17], v[66:67], v[38:39] op_sel_hi:[1,0,1]
	v_pk_fma_f32 v[40:41], v[16:17], v[66:67], v[40:41] op_sel:[0,1,0] op_sel_hi:[1,1,1]
	s_waitcnt lgkmcnt(2)
	v_pk_fma_f32 v[38:39], v[18:19], v[68:69], v[38:39] op_sel_hi:[1,0,1]
	v_pk_fma_f32 v[40:41], v[18:19], v[68:69], v[40:41] op_sel:[0,1,0] op_sel_hi:[1,1,1]
	v_pk_fma_f32 v[38:39], v[20:21], v[70:71], v[38:39] op_sel_hi:[1,0,1]
	v_pk_fma_f32 v[40:41], v[20:21], v[70:71], v[40:41] op_sel:[0,1,0] op_sel_hi:[1,1,1]
	s_waitcnt lgkmcnt(0)
	v_mul_f32_e32 v50, v76, v51
	v_add_f32_dpp v38, v38, v38 row_ror:8 row_mask:0xf bank_mask:0x3 bound_ctrl:1
	v_add_f32_dpp v39, v39, v39 row_ror:8 row_mask:0xf bank_mask:0x3 bound_ctrl:1
	v_add_f32_dpp v38, v40, v40 row_ror:8 row_mask:0xf bank_mask:0xc bound_ctrl:1
	v_add_f32_dpp v39, v41, v41 row_ror:8 row_mask:0xf bank_mask:0xc bound_ctrl:1
	ds_read_b128 v[80:83], v2 offset:19712
	v_add_f32_dpp v38, v38, v38 row_half_mirror row_mask:0xf bank_mask:0x5 bound_ctrl:1
	v_add_f32_dpp v38, v39, v39 row_half_mirror row_mask:0xf bank_mask:0xa bound_ctrl:1
	ds_read_b128 v[84:87], v2 offset:19968
	ds_read_b128 v[88:91], v2 offset:20224
	v_add_f32_dpp v38, v38, v38 quad_perm:[1,0,3,2] row_mask:0xf bank_mask:0xf bound_ctrl:1
	ds_read_b128 v[92:95], v2 offset:20480
	ds_read_b64 v[96:97], v3 offset:29696
	v_add_f32_dpp v38, v38, v38 quad_perm:[2,3,0,1] row_mask:0xf bank_mask:0xf bound_ctrl:1
	ds_read_b128 v[100:103], v1 offset:31024
	v_cmp_gt_f32_e32 vcc, 0x2b8cbccc, v50
	v_fmac_f32_dpp v72, -v38, v50 row_newbcast:0 row_mask:0xf bank_mask:0xf bound_ctrl:1
	v_fmac_f32_dpp v73, -v38, v50 row_newbcast:4 row_mask:0xf bank_mask:0xf bound_ctrl:1
	v_pk_mul_f32 v[44:45], v[72:73], v[76:77] op_sel:[0,1] op_sel_hi:[1,1]
	v_pk_mul_f32 v[48:49], v[44:45], v[78:79] op_sel_hi:[1,0]
	v_rcp_f32_e32 v52, v50
	s_add_u32 s14, s14, 0x1000
	s_addc_u32 s15, s15, 0
	v_fmac_f32_dpp v48, v38, v50 row_newbcast:8 row_mask:0xf bank_mask:0xf bound_ctrl:1
	v_fmac_f32_dpp v49, v38, v50 row_newbcast:12 row_mask:0xf bank_mask:0xf bound_ctrl:1
	s_cbranch_vccnz .Lgd2_rare1_2
.Lgd2_back1_2:
	v_cvt_pk_bf16_f32 v54, v48, v49
	v_pk_mul_f32 v[46:47], v[44:45], v[52:53] op_sel_hi:[1,0]
	v_pk_fma_f32 v[6:7], v[56:57], v[46:47], v[6:7] op_sel_hi:[0,1,1]
	v_pk_fma_f32 v[8:9], v[58:59], v[46:47], v[8:9] op_sel_hi:[0,1,1]
	v_pk_fma_f32 v[10:11], v[60:61], v[46:47], v[10:11] op_sel_hi:[0,1,1]
	v_pk_fma_f32 v[12:13], v[62:63], v[46:47], v[12:13] op_sel_hi:[0,1,1]
	v_pk_fma_f32 v[14:15], v[64:65], v[46:47], v[14:15] op_sel_hi:[0,1,1]
	v_pk_fma_f32 v[16:17], v[66:67], v[46:47], v[16:17] op_sel_hi:[0,1,1]
	v_pk_fma_f32 v[18:19], v[68:69], v[46:47], v[18:19] op_sel_hi:[0,1,1]
	v_pk_fma_f32 v[20:21], v[70:71], v[46:47], v[20:21] op_sel_hi:[0,1,1]
	global_store_dword v154, v54, s[14:15] offset:-4096
	s_waitcnt lgkmcnt(5)
	v_pk_mul_f32 v[38:39], v[6:7], v[80:81] op_sel_hi:[1,0]
	v_pk_mul_f32 v[40:41], v[6:7], v[80:81] op_sel:[0,1] op_sel_hi:[1,1]
	v_pk_fma_f32 v[38:39], v[8:9], v[82:83], v[38:39] op_sel_hi:[1,0,1]
	v_pk_fma_f32 v[40:41], v[8:9], v[82:83], v[40:41] op_sel:[0,1,0] op_sel_hi:[1,1,1]
	s_waitcnt lgkmcnt(4)
	v_pk_fma_f32 v[38:39], v[10:11], v[84:85], v[38:39] op_sel_hi:[1,0,1]
	v_pk_fma_f32 v[40:41], v[10:11], v[84:85], v[40:41] op_sel:[0,1,0] op_sel_hi:[1,1,1]
	v_pk_fma_f32 v[38:39], v[12:13], v[86:87], v[38:39] op_sel_hi:[1,0,1]
	v_pk_fma_f32 v[40:41], v[12:13], v[86:87], v[40:41] op_sel:[0,1,0] op_sel_hi:[1,1,1]
	s_waitcnt lgkmcnt(3)
	v_pk_fma_f32 v[38:39], v[14:15], v[88:89], v[38:39] op_sel_hi:[1,0,1]
	v_pk_fma_f32 v[40:41], v[14:15], v[88:89], v[40:41] op_sel:[0,1,0] op_sel_hi:[1,1,1]
	v_pk_fma_f32 v[38:39], v[16:17], v[90:91], v[38:39] op_sel_hi:[1,0,1]
	v_pk_fma_f32 v[40:41], v[16:17], v[90:91], v[40:41] op_sel:[0,1,0] op_sel_hi:[1,1,1]
	s_waitcnt lgkmcnt(2)
	v_pk_fma_f32 v[38:39], v[18:19], v[92:93], v[38:39] op_sel_hi:[1,0,1]
	v_pk_fma_f32 v[40:41], v[18:19], v[92:93], v[40:41] op_sel:[0,1,0] op_sel_hi:[1,1,1]
	v_pk_fma_f32 v[38:39], v[20:21], v[94:95], v[38:39] op_sel_hi:[1,0,1]
	v_pk_fma_f32 v[40:41], v[20:21], v[94:95], v[40:41] op_sel:[0,1,0] op_sel_hi:[1,1,1]
	s_waitcnt lgkmcnt(0)
	v_mul_f32_e32 v51, v100, v50
	v_add_f32_dpp v38, v38, v38 row_ror:8 row_mask:0xf bank_mask:0x3 bound_ctrl:1
	v_add_f32_dpp v39, v39, v39 row_ror:8 row_mask:0xf bank_mask:0x3 bound_ctrl:1
	v_add_f32_dpp v38, v40, v40 row_ror:8 row_mask:0xf bank_mask:0xc bound_ctrl:1
	v_add_f32_dpp v39, v41, v41 row_ror:8 row_mask:0xf bank_mask:0xc bound_ctrl:1
	ds_read_b128 v[56:59], v2 offset:20736
	v_add_f32_dpp v38, v38, v38 row_half_mirror row_mask:0xf bank_mask:0x5 bound_ctrl:1
	v_add_f32_dpp v38, v39, v39 row_half_mirror row_mask:0xf bank_mask:0xa bound_ctrl:1
	ds_read_b128 v[60:63], v2 offset:20992
	ds_read_b128 v[64:67], v2 offset:21248
	v_add_f32_dpp v38, v38, v38 quad_perm:[1,0,3,2] row_mask:0xf bank_mask:0xf bound_ctrl:1
	ds_read_b128 v[68:71], v2 offset:21504
	ds_read_b64 v[72:73], v3 offset:29952
	v_add_f32_dpp v38, v38, v38 quad_perm:[2,3,0,1] row_mask:0xf bank_mask:0xf bound_ctrl:1
	ds_read_b128 v[76:79], v1 offset:31040
	v_cmp_gt_f32_e32 vcc, 0x2b8cbccc, v51
	v_fmac_f32_dpp v96, -v38, v51 row_newbcast:0 row_mask:0xf bank_mask:0xf bound_ctrl:1
	v_fmac_f32_dpp v97, -v38, v51 row_newbcast:4 row_mask:0xf bank_mask:0xf bound_ctrl:1
	v_pk_mul_f32 v[44:45], v[96:97], v[100:101] op_sel:[0,1] op_sel_hi:[1,1]
	v_pk_mul_f32 v[48:49], v[44:45], v[102:103] op_sel_hi:[1,0]
	v_rcp_f32_e32 v52, v51
	s_add_u32 s14, s14, 0x1000
	s_addc_u32 s15, s15, 0
	v_fmac_f32_dpp v48, v38, v51 row_newbcast:8 row_mask:0xf bank_mask:0xf bound_ctrl:1
	v_fmac_f32_dpp v49, v38, v51 row_newbcast:12 row_mask:0xf bank_mask:0xf bound_ctrl:1
	s_cbranch_vccnz .Lgd2_rare1_3
.Lgd2_back1_3:
	v_cvt_pk_bf16_f32 v54, v48, v49
	v_pk_mul_f32 v[46:47], v[44:45], v[52:53] op_sel_hi:[1,0]
	v_pk_fma_f32 v[6:7], v[80:81], v[46:47], v[6:7] op_sel_hi:[0,1,1]
	v_pk_fma_f32 v[8:9], v[82:83], v[46:47], v[8:9] op_sel_hi:[0,1,1]
	v_pk_fma_f32 v[10:11], v[84:85], v[46:47], v[10:11] op_sel_hi:[0,1,1]
	v_pk_fma_f32 v[12:13], v[86:87], v[46:47], v[12:13] op_sel_hi:[0,1,1]
	v_pk_fma_f32 v[14:15], v[88:89], v[46:47], v[14:15] op_sel_hi:[0,1,1]
	v_pk_fma_f32 v[16:17], v[90:91], v[46:47], v[16:17] op_sel_hi:[0,1,1]
	v_pk_fma_f32 v[18:19], v[92:93], v[46:47], v[18:19] op_sel_hi:[0,1,1]
	v_pk_fma_f32 v[20:21], v[94:95], v[46:47], v[20:21] op_sel_hi:[0,1,1]
	global_store_dword v154, v54, s[14:15] offset:-4096
	s_waitcnt lgkmcnt(5)
	v_pk_mul_f32 v[38:39], v[6:7], v[56:57] op_sel_hi:[1,0]
	v_pk_mul_f32 v[40:41], v[6:7], v[56:57] op_sel:[0,1] op_sel_hi:[1,1]
	v_pk_fma_f32 v[38:39], v[8:9], v[58:59], v[38:39] op_sel_hi:[1,0,1]
	v_pk_fma_f32 v[40:41], v[8:9], v[58:59], v[40:41] op_sel:[0,1,0] op_sel_hi:[1,1,1]
	s_waitcnt lgkmcnt(4)
	v_pk_fma_f32 v[38:39], v[10:11], v[60:61], v[38:39] op_sel_hi:[1,0,1]
	v_pk_fma_f32 v[40:41], v[10:11], v[60:61], v[40:41] op_sel:[0,1,0] op_sel_hi:[1,1,1]
	v_pk_fma_f32 v[38:39], v[12:13], v[62:63], v[38:39] op_sel_hi:[1,0,1]
	v_pk_fma_f32 v[40:41], v[12:13], v[62:63], v[40:41] op_sel:[0,1,0] op_sel_hi:[1,1,1]
	s_waitcnt lgkmcnt(3)
	v_pk_fma_f32 v[38:39], v[14:15], v[64:65], v[38:39] op_sel_hi:[1,0,1]
	v_pk_fma_f32 v[40:41], v[14:15], v[64:65], v[40:41] op_sel:[0,1,0] op_sel_hi:[1,1,1]
	v_pk_fma_f32 v[38:39], v[16:17], v[66:67], v[38:39] op_sel_hi:[1,0,1]
	v_pk_fma_f32 v[40:41], v[16:17], v[66:67], v[40:41] op_sel:[0,1,0] op_sel_hi:[1,1,1]
	s_waitcnt lgkmcnt(2)
	v_pk_fma_f32 v[38:39], v[18:19], v[68:69], v[38:39] op_sel_hi:[1,0,1]
	v_pk_fma_f32 v[40:41], v[18:19], v[68:69], v[40:41] op_sel:[0,1,0] op_sel_hi:[1,1,1]
	v_pk_fma_f32 v[38:39], v[20:21], v[70:71], v[38:39] op_sel_hi:[1,0,1]
	v_pk_fma_f32 v[40:41], v[20:21], v[70:71], v[40:41] op_sel:[0,1,0] op_sel_hi:[1,1,1]
	s_waitcnt lgkmcnt(0)
	v_mul_f32_e32 v50, v76, v51
	v_add_f32_dpp v38, v38, v38 row_ror:8 row_mask:0xf bank_mask:0x3 bound_ctrl:1
	v_add_f32_dpp v39, v39, v39 row_ror:8 row_mask:0xf bank_mask:0x3 bound_ctrl:1
	v_add_f32_dpp v38, v40, v40 row_ror:8 row_mask:0xf bank_mask:0xc bound_ctrl:1
	v_add_f32_dpp v39, v41, v41 row_ror:8 row_mask:0xf bank_mask:0xc bound_ctrl:1
	ds_read_b128 v[80:83], v2 offset:21760
	v_add_f32_dpp v38, v38, v38 row_half_mirror row_mask:0xf bank_mask:0x5 bound_ctrl:1
	v_add_f32_dpp v38, v39, v39 row_half_mirror row_mask:0xf bank_mask:0xa bound_ctrl:1
	ds_read_b128 v[84:87], v2 offset:22016
	ds_read_b128 v[88:91], v2 offset:22272
	v_add_f32_dpp v38, v38, v38 quad_perm:[1,0,3,2] row_mask:0xf bank_mask:0xf bound_ctrl:1
	ds_read_b128 v[92:95], v2 offset:22528
	ds_read_b64 v[96:97], v3 offset:30208
	v_add_f32_dpp v38, v38, v38 quad_perm:[2,3,0,1] row_mask:0xf bank_mask:0xf bound_ctrl:1
	ds_read_b128 v[100:103], v1 offset:31056
	v_cmp_gt_f32_e32 vcc, 0x2b8cbccc, v50
	v_fmac_f32_dpp v72, -v38, v50 row_newbcast:0 row_mask:0xf bank_mask:0xf bound_ctrl:1
	v_fmac_f32_dpp v73, -v38, v50 row_newbcast:4 row_mask:0xf bank_mask:0xf bound_ctrl:1
	v_pk_mul_f32 v[44:45], v[72:73], v[76:77] op_sel:[0,1] op_sel_hi:[1,1]
	v_pk_mul_f32 v[48:49], v[44:45], v[78:79] op_sel_hi:[1,0]
	v_rcp_f32_e32 v52, v50
	s_add_u32 s14, s14, 0x1000
	s_addc_u32 s15, s15, 0
	v_fmac_f32_dpp v48, v38, v50 row_newbcast:8 row_mask:0xf bank_mask:0xf bound_ctrl:1
	v_fmac_f32_dpp v49, v38, v50 row_newbcast:12 row_mask:0xf bank_mask:0xf bound_ctrl:1
	s_cbranch_vccnz .Lgd2_rare1_4
.Lgd2_back1_4:
	v_cvt_pk_bf16_f32 v54, v48, v49
	v_pk_mul_f32 v[46:47], v[44:45], v[52:53] op_sel_hi:[1,0]
	v_pk_fma_f32 v[6:7], v[56:57], v[46:47], v[6:7] op_sel_hi:[0,1,1]
	v_pk_fma_f32 v[8:9], v[58:59], v[46:47], v[8:9] op_sel_hi:[0,1,1]
	v_pk_fma_f32 v[10:11], v[60:61], v[46:47], v[10:11] op_sel_hi:[0,1,1]
	v_pk_fma_f32 v[12:13], v[62:63], v[46:47], v[12:13] op_sel_hi:[0,1,1]
	v_pk_fma_f32 v[14:15], v[64:65], v[46:47], v[14:15] op_sel_hi:[0,1,1]
	v_pk_fma_f32 v[16:17], v[66:67], v[46:47], v[16:17] op_sel_hi:[0,1,1]
	v_pk_fma_f32 v[18:19], v[68:69], v[46:47], v[18:19] op_sel_hi:[0,1,1]
	v_pk_fma_f32 v[20:21], v[70:71], v[46:47], v[20:21] op_sel_hi:[0,1,1]
	global_store_dword v154, v54, s[14:15] offset:-4096
	s_waitcnt lgkmcnt(5)
	v_pk_mul_f32 v[38:39], v[6:7], v[80:81] op_sel_hi:[1,0]
	v_pk_mul_f32 v[40:41], v[6:7], v[80:81] op_sel:[0,1] op_sel_hi:[1,1]
	v_pk_fma_f32 v[38:39], v[8:9], v[82:83], v[38:39] op_sel_hi:[1,0,1]
	v_pk_fma_f32 v[40:41], v[8:9], v[82:83], v[40:41] op_sel:[0,1,0] op_sel_hi:[1,1,1]
	s_waitcnt lgkmcnt(4)
	v_pk_fma_f32 v[38:39], v[10:11], v[84:85], v[38:39] op_sel_hi:[1,0,1]
	v_pk_fma_f32 v[40:41], v[10:11], v[84:85], v[40:41] op_sel:[0,1,0] op_sel_hi:[1,1,1]
	v_pk_fma_f32 v[38:39], v[12:13], v[86:87], v[38:39] op_sel_hi:[1,0,1]
	v_pk_fma_f32 v[40:41], v[12:13], v[86:87], v[40:41] op_sel:[0,1,0] op_sel_hi:[1,1,1]
	s_waitcnt lgkmcnt(3)
	v_pk_fma_f32 v[38:39], v[14:15], v[88:89], v[38:39] op_sel_hi:[1,0,1]
	v_pk_fma_f32 v[40:41], v[14:15], v[88:89], v[40:41] op_sel:[0,1,0] op_sel_hi:[1,1,1]
	v_pk_fma_f32 v[38:39], v[16:17], v[90:91], v[38:39] op_sel_hi:[1,0,1]
	v_pk_fma_f32 v[40:41], v[16:17], v[90:91], v[40:41] op_sel:[0,1,0] op_sel_hi:[1,1,1]
	s_waitcnt lgkmcnt(2)
	v_pk_fma_f32 v[38:39], v[18:19], v[92:93], v[38:39] op_sel_hi:[1,0,1]
	v_pk_fma_f32 v[40:41], v[18:19], v[92:93], v[40:41] op_sel:[0,1,0] op_sel_hi:[1,1,1]
	v_pk_fma_f32 v[38:39], v[20:21], v[94:95], v[38:39] op_sel_hi:[1,0,1]
	v_pk_fma_f32 v[40:41], v[20:21], v[94:95], v[40:41] op_sel:[0,1,0] op_sel_hi:[1,1,1]
	s_waitcnt lgkmcnt(0)
	v_mul_f32_e32 v51, v100, v50
	v_add_f32_dpp v38, v38, v38 row_ror:8 row_mask:0xf bank_mask:0x3 bound_ctrl:1
	v_add_f32_dpp v39, v39, v39 row_ror:8 row_mask:0xf bank_mask:0x3 bound_ctrl:1
	v_add_f32_dpp v38, v40, v40 row_ror:8 row_mask:0xf bank_mask:0xc bound_ctrl:1
	v_add_f32_dpp v39, v41, v41 row_ror:8 row_mask:0xf bank_mask:0xc bound_ctrl:1
	ds_read_b128 v[56:59], v2 offset:22784
	v_add_f32_dpp v38, v38, v38 row_half_mirror row_mask:0xf bank_mask:0x5 bound_ctrl:1
	v_add_f32_dpp v38, v39, v39 row_half_mirror row_mask:0xf bank_mask:0xa bound_ctrl:1
	ds_read_b128 v[60:63], v2 offset:23040
	ds_read_b128 v[64:67], v2 offset:23296
	v_add_f32_dpp v38, v38, v38 quad_perm:[1,0,3,2] row_mask:0xf bank_mask:0xf bound_ctrl:1
	ds_read_b128 v[68:71], v2 offset:23552
	ds_read_b64 v[72:73], v3 offset:30464
	v_add_f32_dpp v38, v38, v38 quad_perm:[2,3,0,1] row_mask:0xf bank_mask:0xf bound_ctrl:1
	ds_read_b128 v[76:79], v1 offset:31072
	v_cmp_gt_f32_e32 vcc, 0x2b8cbccc, v51
	v_fmac_f32_dpp v96, -v38, v51 row_newbcast:0 row_mask:0xf bank_mask:0xf bound_ctrl:1
	v_fmac_f32_dpp v97, -v38, v51 row_newbcast:4 row_mask:0xf bank_mask:0xf bound_ctrl:1
	v_pk_mul_f32 v[44:45], v[96:97], v[100:101] op_sel:[0,1] op_sel_hi:[1,1]
	v_pk_mul_f32 v[48:49], v[44:45], v[102:103] op_sel_hi:[1,0]
	v_rcp_f32_e32 v52, v51
	s_add_u32 s14, s14, 0x1000
	s_addc_u32 s15, s15, 0
	v_fmac_f32_dpp v48, v38, v51 row_newbcast:8 row_mask:0xf bank_mask:0xf bound_ctrl:1
	v_fmac_f32_dpp v49, v38, v51 row_newbcast:12 row_mask:0xf bank_mask:0xf bound_ctrl:1
	s_cbranch_vccnz .Lgd2_rare1_5
.Lgd2_back1_5:
	v_cvt_pk_bf16_f32 v54, v48, v49
	v_pk_mul_f32 v[46:47], v[44:45], v[52:53] op_sel_hi:[1,0]
	v_pk_fma_f32 v[6:7], v[80:81], v[46:47], v[6:7] op_sel_hi:[0,1,1]
	v_pk_fma_f32 v[8:9], v[82:83], v[46:47], v[8:9] op_sel_hi:[0,1,1]
	v_pk_fma_f32 v[10:11], v[84:85], v[46:47], v[10:11] op_sel_hi:[0,1,1]
	v_pk_fma_f32 v[12:13], v[86:87], v[46:47], v[12:13] op_sel_hi:[0,1,1]
	v_pk_fma_f32 v[14:15], v[88:89], v[46:47], v[14:15] op_sel_hi:[0,1,1]
	v_pk_fma_f32 v[16:17], v[90:91], v[46:47], v[16:17] op_sel_hi:[0,1,1]
	v_pk_fma_f32 v[18:19], v[92:93], v[46:47], v[18:19] op_sel_hi:[0,1,1]
	v_pk_fma_f32 v[20:21], v[94:95], v[46:47], v[20:21] op_sel_hi:[0,1,1]
	global_store_dword v154, v54, s[14:15] offset:-4096
	s_waitcnt lgkmcnt(5)
	v_pk_mul_f32 v[38:39], v[6:7], v[56:57] op_sel_hi:[1,0]
	v_pk_mul_f32 v[40:41], v[6:7], v[56:57] op_sel:[0,1] op_sel_hi:[1,1]
	v_pk_fma_f32 v[38:39], v[8:9], v[58:59], v[38:39] op_sel_hi:[1,0,1]
	v_pk_fma_f32 v[40:41], v[8:9], v[58:59], v[40:41] op_sel:[0,1,0] op_sel_hi:[1,1,1]
	s_waitcnt lgkmcnt(4)
	v_pk_fma_f32 v[38:39], v[10:11], v[60:61], v[38:39] op_sel_hi:[1,0,1]
	v_pk_fma_f32 v[40:41], v[10:11], v[60:61], v[40:41] op_sel:[0,1,0] op_sel_hi:[1,1,1]
	v_pk_fma_f32 v[38:39], v[12:13], v[62:63], v[38:39] op_sel_hi:[1,0,1]
	v_pk_fma_f32 v[40:41], v[12:13], v[62:63], v[40:41] op_sel:[0,1,0] op_sel_hi:[1,1,1]
	s_waitcnt lgkmcnt(3)
	v_pk_fma_f32 v[38:39], v[14:15], v[64:65], v[38:39] op_sel_hi:[1,0,1]
	v_pk_fma_f32 v[40:41], v[14:15], v[64:65], v[40:41] op_sel:[0,1,0] op_sel_hi:[1,1,1]
	v_pk_fma_f32 v[38:39], v[16:17], v[66:67], v[38:39] op_sel_hi:[1,0,1]
	v_pk_fma_f32 v[40:41], v[16:17], v[66:67], v[40:41] op_sel:[0,1,0] op_sel_hi:[1,1,1]
	s_waitcnt lgkmcnt(2)
	v_pk_fma_f32 v[38:39], v[18:19], v[68:69], v[38:39] op_sel_hi:[1,0,1]
	v_pk_fma_f32 v[40:41], v[18:19], v[68:69], v[40:41] op_sel:[0,1,0] op_sel_hi:[1,1,1]
	v_pk_fma_f32 v[38:39], v[20:21], v[70:71], v[38:39] op_sel_hi:[1,0,1]
	v_pk_fma_f32 v[40:41], v[20:21], v[70:71], v[40:41] op_sel:[0,1,0] op_sel_hi:[1,1,1]
	s_waitcnt lgkmcnt(0)
	v_mul_f32_e32 v50, v76, v51
	v_add_f32_dpp v38, v38, v38 row_ror:8 row_mask:0xf bank_mask:0x3 bound_ctrl:1
	v_add_f32_dpp v39, v39, v39 row_ror:8 row_mask:0xf bank_mask:0x3 bound_ctrl:1
	v_add_f32_dpp v38, v40, v40 row_ror:8 row_mask:0xf bank_mask:0xc bound_ctrl:1
	v_add_f32_dpp v39, v41, v41 row_ror:8 row_mask:0xf bank_mask:0xc bound_ctrl:1
	ds_read_b128 v[80:83], v2 offset:23808
	v_add_f32_dpp v38, v38, v38 row_half_mirror row_mask:0xf bank_mask:0x5 bound_ctrl:1
	v_add_f32_dpp v38, v39, v39 row_half_mirror row_mask:0xf bank_mask:0xa bound_ctrl:1
	ds_read_b128 v[84:87], v2 offset:24064
	ds_read_b128 v[88:91], v2 offset:24320
	v_add_f32_dpp v38, v38, v38 quad_perm:[1,0,3,2] row_mask:0xf bank_mask:0xf bound_ctrl:1
	ds_read_b128 v[92:95], v2 offset:24576
	ds_read_b64 v[96:97], v3 offset:30720
	v_add_f32_dpp v38, v38, v38 quad_perm:[2,3,0,1] row_mask:0xf bank_mask:0xf bound_ctrl:1
	ds_read_b128 v[100:103], v1 offset:31088
	v_cmp_gt_f32_e32 vcc, 0x2b8cbccc, v50
	v_fmac_f32_dpp v72, -v38, v50 row_newbcast:0 row_mask:0xf bank_mask:0xf bound_ctrl:1
	v_fmac_f32_dpp v73, -v38, v50 row_newbcast:4 row_mask:0xf bank_mask:0xf bound_ctrl:1
	v_pk_mul_f32 v[44:45], v[72:73], v[76:77] op_sel:[0,1] op_sel_hi:[1,1]
	v_pk_mul_f32 v[48:49], v[44:45], v[78:79] op_sel_hi:[1,0]
	v_rcp_f32_e32 v52, v50
	s_add_u32 s14, s14, 0x1000
	s_addc_u32 s15, s15, 0
	v_fmac_f32_dpp v48, v38, v50 row_newbcast:8 row_mask:0xf bank_mask:0xf bound_ctrl:1
	v_fmac_f32_dpp v49, v38, v50 row_newbcast:12 row_mask:0xf bank_mask:0xf bound_ctrl:1
	s_cbranch_vccnz .Lgd2_rare1_6
.Lgd2_back1_6:
	v_cvt_pk_bf16_f32 v54, v48, v49
	v_pk_mul_f32 v[46:47], v[44:45], v[52:53] op_sel_hi:[1,0]
	v_pk_fma_f32 v[6:7], v[56:57], v[46:47], v[6:7] op_sel_hi:[0,1,1]
	v_pk_fma_f32 v[8:9], v[58:59], v[46:47], v[8:9] op_sel_hi:[0,1,1]
	v_pk_fma_f32 v[10:11], v[60:61], v[46:47], v[10:11] op_sel_hi:[0,1,1]
	v_pk_fma_f32 v[12:13], v[62:63], v[46:47], v[12:13] op_sel_hi:[0,1,1]
	v_pk_fma_f32 v[14:15], v[64:65], v[46:47], v[14:15] op_sel_hi:[0,1,1]
	v_pk_fma_f32 v[16:17], v[66:67], v[46:47], v[16:17] op_sel_hi:[0,1,1]
	v_pk_fma_f32 v[18:19], v[68:69], v[46:47], v[18:19] op_sel_hi:[0,1,1]
	v_pk_fma_f32 v[20:21], v[70:71], v[46:47], v[20:21] op_sel_hi:[0,1,1]
	global_store_dword v154, v54, s[14:15] offset:-4096
	s_waitcnt lgkmcnt(5)
	v_pk_mul_f32 v[38:39], v[6:7], v[80:81] op_sel_hi:[1,0]
	v_pk_mul_f32 v[40:41], v[6:7], v[80:81] op_sel:[0,1] op_sel_hi:[1,1]
	v_pk_fma_f32 v[38:39], v[8:9], v[82:83], v[38:39] op_sel_hi:[1,0,1]
	v_pk_fma_f32 v[40:41], v[8:9], v[82:83], v[40:41] op_sel:[0,1,0] op_sel_hi:[1,1,1]
	s_waitcnt lgkmcnt(4)
	v_pk_fma_f32 v[38:39], v[10:11], v[84:85], v[38:39] op_sel_hi:[1,0,1]
	v_pk_fma_f32 v[40:41], v[10:11], v[84:85], v[40:41] op_sel:[0,1,0] op_sel_hi:[1,1,1]
	v_pk_fma_f32 v[38:39], v[12:13], v[86:87], v[38:39] op_sel_hi:[1,0,1]
	v_pk_fma_f32 v[40:41], v[12:13], v[86:87], v[40:41] op_sel:[0,1,0] op_sel_hi:[1,1,1]
	s_waitcnt lgkmcnt(3)
	v_pk_fma_f32 v[38:39], v[14:15], v[88:89], v[38:39] op_sel_hi:[1,0,1]
	v_pk_fma_f32 v[40:41], v[14:15], v[88:89], v[40:41] op_sel:[0,1,0] op_sel_hi:[1,1,1]
	v_pk_fma_f32 v[38:39], v[16:17], v[90:91], v[38:39] op_sel_hi:[1,0,1]
	v_pk_fma_f32 v[40:41], v[16:17], v[90:91], v[40:41] op_sel:[0,1,0] op_sel_hi:[1,1,1]
	s_waitcnt lgkmcnt(2)
	v_pk_fma_f32 v[38:39], v[18:19], v[92:93], v[38:39] op_sel_hi:[1,0,1]
	v_pk_fma_f32 v[40:41], v[18:19], v[92:93], v[40:41] op_sel:[0,1,0] op_sel_hi:[1,1,1]
	v_pk_fma_f32 v[38:39], v[20:21], v[94:95], v[38:39] op_sel_hi:[1,0,1]
	v_pk_fma_f32 v[40:41], v[20:21], v[94:95], v[40:41] op_sel:[0,1,0] op_sel_hi:[1,1,1]
	s_waitcnt lgkmcnt(0)
	v_mul_f32_e32 v51, v100, v50
	v_add_f32_dpp v38, v38, v38 row_ror:8 row_mask:0xf bank_mask:0x3 bound_ctrl:1
	v_add_f32_dpp v39, v39, v39 row_ror:8 row_mask:0xf bank_mask:0x3 bound_ctrl:1
	v_add_f32_dpp v38, v40, v40 row_ror:8 row_mask:0xf bank_mask:0xc bound_ctrl:1
	v_add_f32_dpp v39, v41, v41 row_ror:8 row_mask:0xf bank_mask:0xc bound_ctrl:1
	ds_read_b128 v[56:59], v2 offset:33024
	v_add_f32_dpp v38, v38, v38 row_half_mirror row_mask:0xf bank_mask:0x5 bound_ctrl:1
	v_add_f32_dpp v38, v39, v39 row_half_mirror row_mask:0xf bank_mask:0xa bound_ctrl:1
	ds_read_b128 v[60:63], v2 offset:33280
	ds_read_b128 v[64:67], v2 offset:33536
	v_add_f32_dpp v38, v38, v38 quad_perm:[1,0,3,2] row_mask:0xf bank_mask:0xf bound_ctrl:1
	ds_read_b128 v[68:71], v2 offset:33792
	ds_read_b64 v[72:73], v3 offset:45312
	v_add_f32_dpp v38, v38, v38 quad_perm:[2,3,0,1] row_mask:0xf bank_mask:0xf bound_ctrl:1
	ds_read_b128 v[76:79], v1 offset:47360
	v_cmp_gt_f32_e32 vcc, 0x2b8cbccc, v51
	v_fmac_f32_dpp v96, -v38, v51 row_newbcast:0 row_mask:0xf bank_mask:0xf bound_ctrl:1
	v_fmac_f32_dpp v97, -v38, v51 row_newbcast:4 row_mask:0xf bank_mask:0xf bound_ctrl:1
	v_pk_mul_f32 v[44:45], v[96:97], v[100:101] op_sel:[0,1] op_sel_hi:[1,1]
	v_pk_mul_f32 v[48:49], v[44:45], v[102:103] op_sel_hi:[1,0]
	v_rcp_f32_e32 v52, v51
	s_add_u32 s14, s14, 0x1000
	s_addc_u32 s15, s15, 0
	v_fmac_f32_dpp v48, v38, v51 row_newbcast:8 row_mask:0xf bank_mask:0xf bound_ctrl:1
	v_fmac_f32_dpp v49, v38, v51 row_newbcast:12 row_mask:0xf bank_mask:0xf bound_ctrl:1
	s_cbranch_vccnz .Lgd2_rare1_7
.Lgd2_back1_7:
	v_cvt_pk_bf16_f32 v54, v48, v49
	v_pk_mul_f32 v[46:47], v[44:45], v[52:53] op_sel_hi:[1,0]
	v_pk_fma_f32 v[6:7], v[80:81], v[46:47], v[6:7] op_sel_hi:[0,1,1]
	v_pk_fma_f32 v[8:9], v[82:83], v[46:47], v[8:9] op_sel_hi:[0,1,1]
	v_pk_fma_f32 v[10:11], v[84:85], v[46:47], v[10:11] op_sel_hi:[0,1,1]
	v_pk_fma_f32 v[12:13], v[86:87], v[46:47], v[12:13] op_sel_hi:[0,1,1]
	v_pk_fma_f32 v[14:15], v[88:89], v[46:47], v[14:15] op_sel_hi:[0,1,1]
	v_pk_fma_f32 v[16:17], v[90:91], v[46:47], v[16:17] op_sel_hi:[0,1,1]
	v_pk_fma_f32 v[18:19], v[92:93], v[46:47], v[18:19] op_sel_hi:[0,1,1]
	v_pk_fma_f32 v[20:21], v[94:95], v[46:47], v[20:21] op_sel_hi:[0,1,1]
	global_store_dword v154, v54, s[14:15] offset:-4096
	s_waitcnt vmcnt(8)
	v_lshlrev_b32_e32 v116, 16, v108
	v_lshlrev_b32_e32 v117, 16, v109
	v_and_b32_e32 v118, s17, v108
	v_and_b32_e32 v119, s17, v109
	v_lshlrev_b32_e32 v120, 16, v110
	v_and_b32_e32 v121, s17, v110
	v_lshlrev_b32_e32 v122, 16, v111
	v_and_b32_e32 v123, s17, v111
	v_lshlrev_b32_e32 v124, 16, v112
	v_and_b32_e32 v125, s17, v112
	ds_write_b128 v32, v[116:119] offset:256
	ds_write_b64 v33, v[120:121] offset:256
	ds_write_b64 v34, v[122:123] offset:256
	ds_write_b64 v34, v[124:125] offset:384
	ds_write_b32 v35, v113 offset:256
	s_add_i32 s16, s16, 8
	s_waitcnt lgkmcnt(0)
	s_barrier
	s_cmpk_lt_u32 s16, 0x800
	s_cbranch_scc0 .Lgd2_done
	global_load_dword v108, v36, s[8:9]
	global_load_dword v109, v36, s[8:9] offset:-2048
	global_load_dword v111, v104, s[8:9] offset:2048
	global_load_dword v110, v37, s[10:11]
	global_load_dword v112, v105, s[10:11]
	global_load_dword v113, v106, s[12:13]
	s_add_u32 s8, s8, 0xc000
	s_addc_u32 s9, s9, 0
	s_add_u32 s10, s10, 0x20000
	s_addc_u32 s11, s11, 0
	s_add_u32 s12, s12, 0x400
	s_addc_u32 s13, s13, 0
	s_waitcnt lgkmcnt(5)
	v_pk_mul_f32 v[38:39], v[6:7], v[56:57] op_sel_hi:[1,0]
	v_pk_mul_f32 v[40:41], v[6:7], v[56:57] op_sel:[0,1] op_sel_hi:[1,1]
	v_pk_fma_f32 v[38:39], v[8:9], v[58:59], v[38:39] op_sel_hi:[1,0,1]
	v_pk_fma_f32 v[40:41], v[8:9], v[58:59], v[40:41] op_sel:[0,1,0] op_sel_hi:[1,1,1]
	s_waitcnt lgkmcnt(4)
	v_pk_fma_f32 v[38:39], v[10:11], v[60:61], v[38:39] op_sel_hi:[1,0,1]
	v_pk_fma_f32 v[40:41], v[10:11], v[60:61], v[40:41] op_sel:[0,1,0] op_sel_hi:[1,1,1]
	v_pk_fma_f32 v[38:39], v[12:13], v[62:63], v[38:39] op_sel_hi:[1,0,1]
	v_pk_fma_f32 v[40:41], v[12:13], v[62:63], v[40:41] op_sel:[0,1,0] op_sel_hi:[1,1,1]
	s_waitcnt lgkmcnt(3)
	v_pk_fma_f32 v[38:39], v[14:15], v[64:65], v[38:39] op_sel_hi:[1,0,1]
	v_pk_fma_f32 v[40:41], v[14:15], v[64:65], v[40:41] op_sel:[0,1,0] op_sel_hi:[1,1,1]
	v_pk_fma_f32 v[38:39], v[16:17], v[66:67], v[38:39] op_sel_hi:[1,0,1]
	v_pk_fma_f32 v[40:41], v[16:17], v[66:67], v[40:41] op_sel:[0,1,0] op_sel_hi:[1,1,1]
	s_waitcnt lgkmcnt(2)
	v_pk_fma_f32 v[38:39], v[18:19], v[68:69], v[38:39] op_sel_hi:[1,0,1]
	v_pk_fma_f32 v[40:41], v[18:19], v[68:69], v[40:41] op_sel:[0,1,0] op_sel_hi:[1,1,1]
	v_pk_fma_f32 v[38:39], v[20:21], v[70:71], v[38:39] op_sel_hi:[1,0,1]
	v_pk_fma_f32 v[40:41], v[20:21], v[70:71], v[40:41] op_sel:[0,1,0] op_sel_hi:[1,1,1]
	s_waitcnt lgkmcnt(0)
	v_mul_f32_e32 v50, v76, v51
	v_add_f32_dpp v38, v38, v38 row_ror:8 row_mask:0xf bank_mask:0x3 bound_ctrl:1
	v_add_f32_dpp v39, v39, v39 row_ror:8 row_mask:0xf bank_mask:0x3 bound_ctrl:1
	v_add_f32_dpp v38, v40, v40 row_ror:8 row_mask:0xf bank_mask:0xc bound_ctrl:1
	v_add_f32_dpp v39, v41, v41 row_ror:8 row_mask:0xf bank_mask:0xc bound_ctrl:1
	ds_read_b128 v[80:83], v2 offset:34048
	v_add_f32_dpp v38, v38, v38 row_half_mirror row_mask:0xf bank_mask:0x5 bound_ctrl:1
	v_add_f32_dpp v38, v39, v39 row_half_mirror row_mask:0xf bank_mask:0xa bound_ctrl:1
	ds_read_b128 v[84:87], v2 offset:34304
	ds_read_b128 v[88:91], v2 offset:34560
	v_add_f32_dpp v38, v38, v38 quad_perm:[1,0,3,2] row_mask:0xf bank_mask:0xf bound_ctrl:1
	ds_read_b128 v[92:95], v2 offset:34816
	ds_read_b64 v[96:97], v3 offset:45568
	v_add_f32_dpp v38, v38, v38 quad_perm:[2,3,0,1] row_mask:0xf bank_mask:0xf bound_ctrl:1
	ds_read_b128 v[100:103], v1 offset:47376
	v_cmp_gt_f32_e32 vcc, 0x2b8cbccc, v50
	v_fmac_f32_dpp v72, -v38, v50 row_newbcast:0 row_mask:0xf bank_mask:0xf bound_ctrl:1
	v_fmac_f32_dpp v73, -v38, v50 row_newbcast:4 row_mask:0xf bank_mask:0xf bound_ctrl:1
	v_pk_mul_f32 v[44:45], v[72:73], v[76:77] op_sel:[0,1] op_sel_hi:[1,1]
	v_pk_mul_f32 v[48:49], v[44:45], v[78:79] op_sel_hi:[1,0]
	v_rcp_f32_e32 v52, v50
	s_add_u32 s14, s14, 0x1000
	s_addc_u32 s15, s15, 0
	v_fmac_f32_dpp v48, v38, v50 row_newbcast:8 row_mask:0xf bank_mask:0xf bound_ctrl:1
	v_fmac_f32_dpp v49, v38, v50 row_newbcast:12 row_mask:0xf bank_mask:0xf bound_ctrl:1
	s_cbranch_vccnz .Lgd2_rare2_0
.Lgd2_back2_0:
	v_cvt_pk_bf16_f32 v54, v48, v49
	v_pk_mul_f32 v[46:47], v[44:45], v[52:53] op_sel_hi:[1,0]
	v_pk_fma_f32 v[6:7], v[56:57], v[46:47], v[6:7] op_sel_hi:[0,1,1]
	v_pk_fma_f32 v[8:9], v[58:59], v[46:47], v[8:9] op_sel_hi:[0,1,1]
	v_pk_fma_f32 v[10:11], v[60:61], v[46:47], v[10:11] op_sel_hi:[0,1,1]
	v_pk_fma_f32 v[12:13], v[62:63], v[46:47], v[12:13] op_sel_hi:[0,1,1]
	v_pk_fma_f32 v[14:15], v[64:65], v[46:47], v[14:15] op_sel_hi:[0,1,1]
	v_pk_fma_f32 v[16:17], v[66:67], v[46:47], v[16:17] op_sel_hi:[0,1,1]
	v_pk_fma_f32 v[18:19], v[68:69], v[46:47], v[18:19] op_sel_hi:[0,1,1]
	v_pk_fma_f32 v[20:21], v[70:71], v[46:47], v[20:21] op_sel_hi:[0,1,1]
	global_store_dword v154, v54, s[14:15] offset:-4096
	s_waitcnt lgkmcnt(5)
	v_pk_mul_f32 v[38:39], v[6:7], v[80:81] op_sel_hi:[1,0]
	v_pk_mul_f32 v[40:41], v[6:7], v[80:81] op_sel:[0,1] op_sel_hi:[1,1]
	v_pk_fma_f32 v[38:39], v[8:9], v[82:83], v[38:39] op_sel_hi:[1,0,1]
	v_pk_fma_f32 v[40:41], v[8:9], v[82:83], v[40:41] op_sel:[0,1,0] op_sel_hi:[1,1,1]
	s_waitcnt lgkmcnt(4)
	v_pk_fma_f32 v[38:39], v[10:11], v[84:85], v[38:39] op_sel_hi:[1,0,1]
	v_pk_fma_f32 v[40:41], v[10:11], v[84:85], v[40:41] op_sel:[0,1,0] op_sel_hi:[1,1,1]
	v_pk_fma_f32 v[38:39], v[12:13], v[86:87], v[38:39] op_sel_hi:[1,0,1]
	v_pk_fma_f32 v[40:41], v[12:13], v[86:87], v[40:41] op_sel:[0,1,0] op_sel_hi:[1,1,1]
	s_waitcnt lgkmcnt(3)
	v_pk_fma_f32 v[38:39], v[14:15], v[88:89], v[38:39] op_sel_hi:[1,0,1]
	v_pk_fma_f32 v[40:41], v[14:15], v[88:89], v[40:41] op_sel:[0,1,0] op_sel_hi:[1,1,1]
	v_pk_fma_f32 v[38:39], v[16:17], v[90:91], v[38:39] op_sel_hi:[1,0,1]
	v_pk_fma_f32 v[40:41], v[16:17], v[90:91], v[40:41] op_sel:[0,1,0] op_sel_hi:[1,1,1]
	s_waitcnt lgkmcnt(2)
	v_pk_fma_f32 v[38:39], v[18:19], v[92:93], v[38:39] op_sel_hi:[1,0,1]
	v_pk_fma_f32 v[40:41], v[18:19], v[92:93], v[40:41] op_sel:[0,1,0] op_sel_hi:[1,1,1]
	v_pk_fma_f32 v[38:39], v[20:21], v[94:95], v[38:39] op_sel_hi:[1,0,1]
	v_pk_fma_f32 v[40:41], v[20:21], v[94:95], v[40:41] op_sel:[0,1,0] op_sel_hi:[1,1,1]
	s_waitcnt lgkmcnt(0)
	v_mul_f32_e32 v51, v100, v50
	v_add_f32_dpp v38, v38, v38 row_ror:8 row_mask:0xf bank_mask:0x3 bound_ctrl:1
	v_add_f32_dpp v39, v39, v39 row_ror:8 row_mask:0xf bank_mask:0x3 bound_ctrl:1
	v_add_f32_dpp v38, v40, v40 row_ror:8 row_mask:0xf bank_mask:0xc bound_ctrl:1
	v_add_f32_dpp v39, v41, v41 row_ror:8 row_mask:0xf bank_mask:0xc bound_ctrl:1
	ds_read_b128 v[56:59], v2 offset:35072
	v_add_f32_dpp v38, v38, v38 row_half_mirror row_mask:0xf bank_mask:0x5 bound_ctrl:1
	v_add_f32_dpp v38, v39, v39 row_half_mirror row_mask:0xf bank_mask:0xa bound_ctrl:1
	ds_read_b128 v[60:63], v2 offset:35328
	ds_read_b128 v[64:67], v2 offset:35584
	v_add_f32_dpp v38, v38, v38 quad_perm:[1,0,3,2] row_mask:0xf bank_mask:0xf bound_ctrl:1
	ds_read_b128 v[68:71], v2 offset:35840
	ds_read_b64 v[72:73], v3 offset:45824
	v_add_f32_dpp v38, v38, v38 quad_perm:[2,3,0,1] row_mask:0xf bank_mask:0xf bound_ctrl:1
	ds_read_b128 v[76:79], v1 offset:47392
	v_cmp_gt_f32_e32 vcc, 0x2b8cbccc, v51
	v_fmac_f32_dpp v96, -v38, v51 row_newbcast:0 row_mask:0xf bank_mask:0xf bound_ctrl:1
	v_fmac_f32_dpp v97, -v38, v51 row_newbcast:4 row_mask:0xf bank_mask:0xf bound_ctrl:1
	v_pk_mul_f32 v[44:45], v[96:97], v[100:101] op_sel:[0,1] op_sel_hi:[1,1]
	v_pk_mul_f32 v[48:49], v[44:45], v[102:103] op_sel_hi:[1,0]
	v_rcp_f32_e32 v52, v51
	s_add_u32 s14, s14, 0x1000
	s_addc_u32 s15, s15, 0
	v_fmac_f32_dpp v48, v38, v51 row_newbcast:8 row_mask:0xf bank_mask:0xf bound_ctrl:1
	v_fmac_f32_dpp v49, v38, v51 row_newbcast:12 row_mask:0xf bank_mask:0xf bound_ctrl:1
	s_cbranch_vccnz .Lgd2_rare2_1
.Lgd2_back2_1:
	v_cvt_pk_bf16_f32 v54, v48, v49
	v_pk_mul_f32 v[46:47], v[44:45], v[52:53] op_sel_hi:[1,0]
	v_pk_fma_f32 v[6:7], v[80:81], v[46:47], v[6:7] op_sel_hi:[0,1,1]
	v_pk_fma_f32 v[8:9], v[82:83], v[46:47], v[8:9] op_sel_hi:[0,1,1]
	v_pk_fma_f32 v[10:11], v[84:85], v[46:47], v[10:11] op_sel_hi:[0,1,1]
	v_pk_fma_f32 v[12:13], v[86:87], v[46:47], v[12:13] op_sel_hi:[0,1,1]
	v_pk_fma_f32 v[14:15], v[88:89], v[46:47], v[14:15] op_sel_hi:[0,1,1]
	v_pk_fma_f32 v[16:17], v[90:91], v[46:47], v[16:17] op_sel_hi:[0,1,1]
	v_pk_fma_f32 v[18:19], v[92:93], v[46:47], v[18:19] op_sel_hi:[0,1,1]
	v_pk_fma_f32 v[20:21], v[94:95], v[46:47], v[20:21] op_sel_hi:[0,1,1]
	global_store_dword v154, v54, s[14:15] offset:-4096
	s_waitcnt lgkmcnt(5)
	v_pk_mul_f32 v[38:39], v[6:7], v[56:57] op_sel_hi:[1,0]
	v_pk_mul_f32 v[40:41], v[6:7], v[56:57] op_sel:[0,1] op_sel_hi:[1,1]
	v_pk_fma_f32 v[38:39], v[8:9], v[58:59], v[38:39] op_sel_hi:[1,0,1]
	v_pk_fma_f32 v[40:41], v[8:9], v[58:59], v[40:41] op_sel:[0,1,0] op_sel_hi:[1,1,1]
	s_waitcnt lgkmcnt(4)
	v_pk_fma_f32 v[38:39], v[10:11], v[60:61], v[38:39] op_sel_hi:[1,0,1]
	v_pk_fma_f32 v[40:41], v[10:11], v[60:61], v[40:41] op_sel:[0,1,0] op_sel_hi:[1,1,1]
	v_pk_fma_f32 v[38:39], v[12:13], v[62:63], v[38:39] op_sel_hi:[1,0,1]
	v_pk_fma_f32 v[40:41], v[12:13], v[62:63], v[40:41] op_sel:[0,1,0] op_sel_hi:[1,1,1]
	s_waitcnt lgkmcnt(3)
	v_pk_fma_f32 v[38:39], v[14:15], v[64:65], v[38:39] op_sel_hi:[1,0,1]
	v_pk_fma_f32 v[40:41], v[14:15], v[64:65], v[40:41] op_sel:[0,1,0] op_sel_hi:[1,1,1]
	v_pk_fma_f32 v[38:39], v[16:17], v[66:67], v[38:39] op_sel_hi:[1,0,1]
	v_pk_fma_f32 v[40:41], v[16:17], v[66:67], v[40:41] op_sel:[0,1,0] op_sel_hi:[1,1,1]
	s_waitcnt lgkmcnt(2)
	v_pk_fma_f32 v[38:39], v[18:19], v[68:69], v[38:39] op_sel_hi:[1,0,1]
	v_pk_fma_f32 v[40:41], v[18:19], v[68:69], v[40:41] op_sel:[0,1,0] op_sel_hi:[1,1,1]
	v_pk_fma_f32 v[38:39], v[20:21], v[70:71], v[38:39] op_sel_hi:[1,0,1]
	v_pk_fma_f32 v[40:41], v[20:21], v[70:71], v[40:41] op_sel:[0,1,0] op_sel_hi:[1,1,1]
	s_waitcnt lgkmcnt(0)
	v_mul_f32_e32 v50, v76, v51
	v_add_f32_dpp v38, v38, v38 row_ror:8 row_mask:0xf bank_mask:0x3 bound_ctrl:1
	v_add_f32_dpp v39, v39, v39 row_ror:8 row_mask:0xf bank_mask:0x3 bound_ctrl:1
	v_add_f32_dpp v38, v40, v40 row_ror:8 row_mask:0xf bank_mask:0xc bound_ctrl:1
	v_add_f32_dpp v39, v41, v41 row_ror:8 row_mask:0xf bank_mask:0xc bound_ctrl:1
	ds_read_b128 v[80:83], v2 offset:36096
	v_add_f32_dpp v38, v38, v38 row_half_mirror row_mask:0xf bank_mask:0x5 bound_ctrl:1
	v_add_f32_dpp v38, v39, v39 row_half_mirror row_mask:0xf bank_mask:0xa bound_ctrl:1
	ds_read_b128 v[84:87], v2 offset:36352
	ds_read_b128 v[88:91], v2 offset:36608
	v_add_f32_dpp v38, v38, v38 quad_perm:[1,0,3,2] row_mask:0xf bank_mask:0xf bound_ctrl:1
	ds_read_b128 v[92:95], v2 offset:36864
	ds_read_b64 v[96:97], v3 offset:46080
	v_add_f32_dpp v38, v38, v38 quad_perm:[2,3,0,1] row_mask:0xf bank_mask:0xf bound_ctrl:1
	ds_read_b128 v[100:103], v1 offset:47408
	v_cmp_gt_f32_e32 vcc, 0x2b8cbccc, v50
	v_fmac_f32_dpp v72, -v38, v50 row_newbcast:0 row_mask:0xf bank_mask:0xf bound_ctrl:1
	v_fmac_f32_dpp v73, -v38, v50 row_newbcast:4 row_mask:0xf bank_mask:0xf bound_ctrl:1
	v_pk_mul_f32 v[44:45], v[72:73], v[76:77] op_sel:[0,1] op_sel_hi:[1,1]
	v_pk_mul_f32 v[48:49], v[44:45], v[78:79] op_sel_hi:[1,0]
	v_rcp_f32_e32 v52, v50
	s_add_u32 s14, s14, 0x1000
	s_addc_u32 s15, s15, 0
	v_fmac_f32_dpp v48, v38, v50 row_newbcast:8 row_mask:0xf bank_mask:0xf bound_ctrl:1
	v_fmac_f32_dpp v49, v38, v50 row_newbcast:12 row_mask:0xf bank_mask:0xf bound_ctrl:1
	s_cbranch_vccnz .Lgd2_rare2_2
.Lgd2_back2_2:
	v_cvt_pk_bf16_f32 v54, v48, v49
	v_pk_mul_f32 v[46:47], v[44:45], v[52:53] op_sel_hi:[1,0]
	v_pk_fma_f32 v[6:7], v[56:57], v[46:47], v[6:7] op_sel_hi:[0,1,1]
	v_pk_fma_f32 v[8:9], v[58:59], v[46:47], v[8:9] op_sel_hi:[0,1,1]
	v_pk_fma_f32 v[10:11], v[60:61], v[46:47], v[10:11] op_sel_hi:[0,1,1]
	v_pk_fma_f32 v[12:13], v[62:63], v[46:47], v[12:13] op_sel_hi:[0,1,1]
	v_pk_fma_f32 v[14:15], v[64:65], v[46:47], v[14:15] op_sel_hi:[0,1,1]
	v_pk_fma_f32 v[16:17], v[66:67], v[46:47], v[16:17] op_sel_hi:[0,1,1]
	v_pk_fma_f32 v[18:19], v[68:69], v[46:47], v[18:19] op_sel_hi:[0,1,1]
	v_pk_fma_f32 v[20:21], v[70:71], v[46:47], v[20:21] op_sel_hi:[0,1,1]
	global_store_dword v154, v54, s[14:15] offset:-4096
	s_waitcnt lgkmcnt(5)
	v_pk_mul_f32 v[38:39], v[6:7], v[80:81] op_sel_hi:[1,0]
	v_pk_mul_f32 v[40:41], v[6:7], v[80:81] op_sel:[0,1] op_sel_hi:[1,1]
	v_pk_fma_f32 v[38:39], v[8:9], v[82:83], v[38:39] op_sel_hi:[1,0,1]
	v_pk_fma_f32 v[40:41], v[8:9], v[82:83], v[40:41] op_sel:[0,1,0] op_sel_hi:[1,1,1]
	s_waitcnt lgkmcnt(4)
	v_pk_fma_f32 v[38:39], v[10:11], v[84:85], v[38:39] op_sel_hi:[1,0,1]
	v_pk_fma_f32 v[40:41], v[10:11], v[84:85], v[40:41] op_sel:[0,1,0] op_sel_hi:[1,1,1]
	v_pk_fma_f32 v[38:39], v[12:13], v[86:87], v[38:39] op_sel_hi:[1,0,1]
	v_pk_fma_f32 v[40:41], v[12:13], v[86:87], v[40:41] op_sel:[0,1,0] op_sel_hi:[1,1,1]
	s_waitcnt lgkmcnt(3)
	v_pk_fma_f32 v[38:39], v[14:15], v[88:89], v[38:39] op_sel_hi:[1,0,1]
	v_pk_fma_f32 v[40:41], v[14:15], v[88:89], v[40:41] op_sel:[0,1,0] op_sel_hi:[1,1,1]
	v_pk_fma_f32 v[38:39], v[16:17], v[90:91], v[38:39] op_sel_hi:[1,0,1]
	v_pk_fma_f32 v[40:41], v[16:17], v[90:91], v[40:41] op_sel:[0,1,0] op_sel_hi:[1,1,1]
	s_waitcnt lgkmcnt(2)
	v_pk_fma_f32 v[38:39], v[18:19], v[92:93], v[38:39] op_sel_hi:[1,0,1]
	v_pk_fma_f32 v[40:41], v[18:19], v[92:93], v[40:41] op_sel:[0,1,0] op_sel_hi:[1,1,1]
	v_pk_fma_f32 v[38:39], v[20:21], v[94:95], v[38:39] op_sel_hi:[1,0,1]
	v_pk_fma_f32 v[40:41], v[20:21], v[94:95], v[40:41] op_sel:[0,1,0] op_sel_hi:[1,1,1]
	s_waitcnt lgkmcnt(0)
	v_mul_f32_e32 v51, v100, v50
	v_add_f32_dpp v38, v38, v38 row_ror:8 row_mask:0xf bank_mask:0x3 bound_ctrl:1
	v_add_f32_dpp v39, v39, v39 row_ror:8 row_mask:0xf bank_mask:0x3 bound_ctrl:1
	v_add_f32_dpp v38, v40, v40 row_ror:8 row_mask:0xf bank_mask:0xc bound_ctrl:1
	v_add_f32_dpp v39, v41, v41 row_ror:8 row_mask:0xf bank_mask:0xc bound_ctrl:1
	ds_read_b128 v[56:59], v2 offset:37120
	v_add_f32_dpp v38, v38, v38 row_half_mirror row_mask:0xf bank_mask:0x5 bound_ctrl:1
	v_add_f32_dpp v38, v39, v39 row_half_mirror row_mask:0xf bank_mask:0xa bound_ctrl:1
	ds_read_b128 v[60:63], v2 offset:37376
	ds_read_b128 v[64:67], v2 offset:37632
	v_add_f32_dpp v38, v38, v38 quad_perm:[1,0,3,2] row_mask:0xf bank_mask:0xf bound_ctrl:1
	ds_read_b128 v[68:71], v2 offset:37888
	ds_read_b64 v[72:73], v3 offset:46336
	v_add_f32_dpp v38, v38, v38 quad_perm:[2,3,0,1] row_mask:0xf bank_mask:0xf bound_ctrl:1
	ds_read_b128 v[76:79], v1 offset:47424
	v_cmp_gt_f32_e32 vcc, 0x2b8cbccc, v51
	v_fmac_f32_dpp v96, -v38, v51 row_newbcast:0 row_mask:0xf bank_mask:0xf bound_ctrl:1
	v_fmac_f32_dpp v97, -v38, v51 row_newbcast:4 row_mask:0xf bank_mask:0xf bound_ctrl:1
	v_pk_mul_f32 v[44:45], v[96:97], v[100:101] op_sel:[0,1] op_sel_hi:[1,1]
	v_pk_mul_f32 v[48:49], v[44:45], v[102:103] op_sel_hi:[1,0]
	v_rcp_f32_e32 v52, v51
	s_add_u32 s14, s14, 0x1000
	s_addc_u32 s15, s15, 0
	v_fmac_f32_dpp v48, v38, v51 row_newbcast:8 row_mask:0xf bank_mask:0xf bound_ctrl:1
	v_fmac_f32_dpp v49, v38, v51 row_newbcast:12 row_mask:0xf bank_mask:0xf bound_ctrl:1
	s_cbranch_vccnz .Lgd2_rare2_3
.Lgd2_back2_3:
	v_cvt_pk_bf16_f32 v54, v48, v49
	v_pk_mul_f32 v[46:47], v[44:45], v[52:53] op_sel_hi:[1,0]
	v_pk_fma_f32 v[6:7], v[80:81], v[46:47], v[6:7] op_sel_hi:[0,1,1]
	v_pk_fma_f32 v[8:9], v[82:83], v[46:47], v[8:9] op_sel_hi:[0,1,1]
	v_pk_fma_f32 v[10:11], v[84:85], v[46:47], v[10:11] op_sel_hi:[0,1,1]
	v_pk_fma_f32 v[12:13], v[86:87], v[46:47], v[12:13] op_sel_hi:[0,1,1]
	v_pk_fma_f32 v[14:15], v[88:89], v[46:47], v[14:15] op_sel_hi:[0,1,1]
	v_pk_fma_f32 v[16:17], v[90:91], v[46:47], v[16:17] op_sel_hi:[0,1,1]
	v_pk_fma_f32 v[18:19], v[92:93], v[46:47], v[18:19] op_sel_hi:[0,1,1]
	v_pk_fma_f32 v[20:21], v[94:95], v[46:47], v[20:21] op_sel_hi:[0,1,1]
	global_store_dword v154, v54, s[14:15] offset:-4096
	s_waitcnt lgkmcnt(5)
	v_pk_mul_f32 v[38:39], v[6:7], v[56:57] op_sel_hi:[1,0]
	v_pk_mul_f32 v[40:41], v[6:7], v[56:57] op_sel:[0,1] op_sel_hi:[1,1]
	v_pk_fma_f32 v[38:39], v[8:9], v[58:59], v[38:39] op_sel_hi:[1,0,1]
	v_pk_fma_f32 v[40:41], v[8:9], v[58:59], v[40:41] op_sel:[0,1,0] op_sel_hi:[1,1,1]
	s_waitcnt lgkmcnt(4)
	v_pk_fma_f32 v[38:39], v[10:11], v[60:61], v[38:39] op_sel_hi:[1,0,1]
	v_pk_fma_f32 v[40:41], v[10:11], v[60:61], v[40:41] op_sel:[0,1,0] op_sel_hi:[1,1,1]
	v_pk_fma_f32 v[38:39], v[12:13], v[62:63], v[38:39] op_sel_hi:[1,0,1]
	v_pk_fma_f32 v[40:41], v[12:13], v[62:63], v[40:41] op_sel:[0,1,0] op_sel_hi:[1,1,1]
	s_waitcnt lgkmcnt(3)
	v_pk_fma_f32 v[38:39], v[14:15], v[64:65], v[38:39] op_sel_hi:[1,0,1]
	v_pk_fma_f32 v[40:41], v[14:15], v[64:65], v[40:41] op_sel:[0,1,0] op_sel_hi:[1,1,1]
	v_pk_fma_f32 v[38:39], v[16:17], v[66:67], v[38:39] op_sel_hi:[1,0,1]
	v_pk_fma_f32 v[40:41], v[16:17], v[66:67], v[40:41] op_sel:[0,1,0] op_sel_hi:[1,1,1]
	s_waitcnt lgkmcnt(2)
	v_pk_fma_f32 v[38:39], v[18:19], v[68:69], v[38:39] op_sel_hi:[1,0,1]
	v_pk_fma_f32 v[40:41], v[18:19], v[68:69], v[40:41] op_sel:[0,1,0] op_sel_hi:[1,1,1]
	v_pk_fma_f32 v[38:39], v[20:21], v[70:71], v[38:39] op_sel_hi:[1,0,1]
	v_pk_fma_f32 v[40:41], v[20:21], v[70:71], v[40:41] op_sel:[0,1,0] op_sel_hi:[1,1,1]
	s_waitcnt lgkmcnt(0)
	v_mul_f32_e32 v50, v76, v51
	v_add_f32_dpp v38, v38, v38 row_ror:8 row_mask:0xf bank_mask:0x3 bound_ctrl:1
	v_add_f32_dpp v39, v39, v39 row_ror:8 row_mask:0xf bank_mask:0x3 bound_ctrl:1
	v_add_f32_dpp v38, v40, v40 row_ror:8 row_mask:0xf bank_mask:0xc bound_ctrl:1
	v_add_f32_dpp v39, v41, v41 row_ror:8 row_mask:0xf bank_mask:0xc bound_ctrl:1
	ds_read_b128 v[80:83], v2 offset:38144
	v_add_f32_dpp v38, v38, v38 row_half_mirror row_mask:0xf bank_mask:0x5 bound_ctrl:1
	v_add_f32_dpp v38, v39, v39 row_half_mirror row_mask:0xf bank_mask:0xa bound_ctrl:1
	ds_read_b128 v[84:87], v2 offset:38400
	ds_read_b128 v[88:91], v2 offset:38656
	v_add_f32_dpp v38, v38, v38 quad_perm:[1,0,3,2] row_mask:0xf bank_mask:0xf bound_ctrl:1
	ds_read_b128 v[92:95], v2 offset:38912
	ds_read_b64 v[96:97], v3 offset:46592
	v_add_f32_dpp v38, v38, v38 quad_perm:[2,3,0,1] row_mask:0xf bank_mask:0xf bound_ctrl:1
	ds_read_b128 v[100:103], v1 offset:47440
	v_cmp_gt_f32_e32 vcc, 0x2b8cbccc, v50
	v_fmac_f32_dpp v72, -v38, v50 row_newbcast:0 row_mask:0xf bank_mask:0xf bound_ctrl:1
	v_fmac_f32_dpp v73, -v38, v50 row_newbcast:4 row_mask:0xf bank_mask:0xf bound_ctrl:1
	v_pk_mul_f32 v[44:45], v[72:73], v[76:77] op_sel:[0,1] op_sel_hi:[1,1]
	v_pk_mul_f32 v[48:49], v[44:45], v[78:79] op_sel_hi:[1,0]
	v_rcp_f32_e32 v52, v50
	s_add_u32 s14, s14, 0x1000
	s_addc_u32 s15, s15, 0
	v_fmac_f32_dpp v48, v38, v50 row_newbcast:8 row_mask:0xf bank_mask:0xf bound_ctrl:1
	v_fmac_f32_dpp v49, v38, v50 row_newbcast:12 row_mask:0xf bank_mask:0xf bound_ctrl:1
	s_cbranch_vccnz .Lgd2_rare2_4
.Lgd2_back2_4:
	v_cvt_pk_bf16_f32 v54, v48, v49
	v_pk_mul_f32 v[46:47], v[44:45], v[52:53] op_sel_hi:[1,0]
	v_pk_fma_f32 v[6:7], v[56:57], v[46:47], v[6:7] op_sel_hi:[0,1,1]
	v_pk_fma_f32 v[8:9], v[58:59], v[46:47], v[8:9] op_sel_hi:[0,1,1]
	v_pk_fma_f32 v[10:11], v[60:61], v[46:47], v[10:11] op_sel_hi:[0,1,1]
	v_pk_fma_f32 v[12:13], v[62:63], v[46:47], v[12:13] op_sel_hi:[0,1,1]
	v_pk_fma_f32 v[14:15], v[64:65], v[46:47], v[14:15] op_sel_hi:[0,1,1]
	v_pk_fma_f32 v[16:17], v[66:67], v[46:47], v[16:17] op_sel_hi:[0,1,1]
	v_pk_fma_f32 v[18:19], v[68:69], v[46:47], v[18:19] op_sel_hi:[0,1,1]
	v_pk_fma_f32 v[20:21], v[70:71], v[46:47], v[20:21] op_sel_hi:[0,1,1]
	global_store_dword v154, v54, s[14:15] offset:-4096
	s_waitcnt lgkmcnt(5)
	v_pk_mul_f32 v[38:39], v[6:7], v[80:81] op_sel_hi:[1,0]
	v_pk_mul_f32 v[40:41], v[6:7], v[80:81] op_sel:[0,1] op_sel_hi:[1,1]
	v_pk_fma_f32 v[38:39], v[8:9], v[82:83], v[38:39] op_sel_hi:[1,0,1]
	v_pk_fma_f32 v[40:41], v[8:9], v[82:83], v[40:41] op_sel:[0,1,0] op_sel_hi:[1,1,1]
	s_waitcnt lgkmcnt(4)
	v_pk_fma_f32 v[38:39], v[10:11], v[84:85], v[38:39] op_sel_hi:[1,0,1]
	v_pk_fma_f32 v[40:41], v[10:11], v[84:85], v[40:41] op_sel:[0,1,0] op_sel_hi:[1,1,1]
	v_pk_fma_f32 v[38:39], v[12:13], v[86:87], v[38:39] op_sel_hi:[1,0,1]
	v_pk_fma_f32 v[40:41], v[12:13], v[86:87], v[40:41] op_sel:[0,1,0] op_sel_hi:[1,1,1]
	s_waitcnt lgkmcnt(3)
	v_pk_fma_f32 v[38:39], v[14:15], v[88:89], v[38:39] op_sel_hi:[1,0,1]
	v_pk_fma_f32 v[40:41], v[14:15], v[88:89], v[40:41] op_sel:[0,1,0] op_sel_hi:[1,1,1]
	v_pk_fma_f32 v[38:39], v[16:17], v[90:91], v[38:39] op_sel_hi:[1,0,1]
	v_pk_fma_f32 v[40:41], v[16:17], v[90:91], v[40:41] op_sel:[0,1,0] op_sel_hi:[1,1,1]
	s_waitcnt lgkmcnt(2)
	v_pk_fma_f32 v[38:39], v[18:19], v[92:93], v[38:39] op_sel_hi:[1,0,1]
	v_pk_fma_f32 v[40:41], v[18:19], v[92:93], v[40:41] op_sel:[0,1,0] op_sel_hi:[1,1,1]
	v_pk_fma_f32 v[38:39], v[20:21], v[94:95], v[38:39] op_sel_hi:[1,0,1]
	v_pk_fma_f32 v[40:41], v[20:21], v[94:95], v[40:41] op_sel:[0,1,0] op_sel_hi:[1,1,1]
	s_waitcnt lgkmcnt(0)
	v_mul_f32_e32 v51, v100, v50
	v_add_f32_dpp v38, v38, v38 row_ror:8 row_mask:0xf bank_mask:0x3 bound_ctrl:1
	v_add_f32_dpp v39, v39, v39 row_ror:8 row_mask:0xf bank_mask:0x3 bound_ctrl:1
	v_add_f32_dpp v38, v40, v40 row_ror:8 row_mask:0xf bank_mask:0xc bound_ctrl:1
	v_add_f32_dpp v39, v41, v41 row_ror:8 row_mask:0xf bank_mask:0xc bound_ctrl:1
	ds_read_b128 v[56:59], v2 offset:39168
	v_add_f32_dpp v38, v38, v38 row_half_mirror row_mask:0xf bank_mask:0x5 bound_ctrl:1
	v_add_f32_dpp v38, v39, v39 row_half_mirror row_mask:0xf bank_mask:0xa bound_ctrl:1
	ds_read_b128 v[60:63], v2 offset:39424
	ds_read_b128 v[64:67], v2 offset:39680
	v_add_f32_dpp v38, v38, v38 quad_perm:[1,0,3,2] row_mask:0xf bank_mask:0xf bound_ctrl:1
	ds_read_b128 v[68:71], v2 offset:39936
	ds_read_b64 v[72:73], v3 offset:46848
	v_add_f32_dpp v38, v38, v38 quad_perm:[2,3,0,1] row_mask:0xf bank_mask:0xf bound_ctrl:1
	ds_read_b128 v[76:79], v1 offset:47456
	v_cmp_gt_f32_e32 vcc, 0x2b8cbccc, v51
	v_fmac_f32_dpp v96, -v38, v51 row_newbcast:0 row_mask:0xf bank_mask:0xf bound_ctrl:1
	v_fmac_f32_dpp v97, -v38, v51 row_newbcast:4 row_mask:0xf bank_mask:0xf bound_ctrl:1
	v_pk_mul_f32 v[44:45], v[96:97], v[100:101] op_sel:[0,1] op_sel_hi:[1,1]
	v_pk_mul_f32 v[48:49], v[44:45], v[102:103] op_sel_hi:[1,0]
	v_rcp_f32_e32 v52, v51
	s_add_u32 s14, s14, 0x1000
	s_addc_u32 s15, s15, 0
	v_fmac_f32_dpp v48, v38, v51 row_newbcast:8 row_mask:0xf bank_mask:0xf bound_ctrl:1
	v_fmac_f32_dpp v49, v38, v51 row_newbcast:12 row_mask:0xf bank_mask:0xf bound_ctrl:1
	s_cbranch_vccnz .Lgd2_rare2_5
.Lgd2_back2_5:
	v_cvt_pk_bf16_f32 v54, v48, v49
	v_pk_mul_f32 v[46:47], v[44:45], v[52:53] op_sel_hi:[1,0]
	v_pk_fma_f32 v[6:7], v[80:81], v[46:47], v[6:7] op_sel_hi:[0,1,1]
	v_pk_fma_f32 v[8:9], v[82:83], v[46:47], v[8:9] op_sel_hi:[0,1,1]
	v_pk_fma_f32 v[10:11], v[84:85], v[46:47], v[10:11] op_sel_hi:[0,1,1]
	v_pk_fma_f32 v[12:13], v[86:87], v[46:47], v[12:13] op_sel_hi:[0,1,1]
	v_pk_fma_f32 v[14:15], v[88:89], v[46:47], v[14:15] op_sel_hi:[0,1,1]
	v_pk_fma_f32 v[16:17], v[90:91], v[46:47], v[16:17] op_sel_hi:[0,1,1]
	v_pk_fma_f32 v[18:19], v[92:93], v[46:47], v[18:19] op_sel_hi:[0,1,1]
	v_pk_fma_f32 v[20:21], v[94:95], v[46:47], v[20:21] op_sel_hi:[0,1,1]
	global_store_dword v154, v54, s[14:15] offset:-4096
	s_waitcnt lgkmcnt(5)
	v_pk_mul_f32 v[38:39], v[6:7], v[56:57] op_sel_hi:[1,0]
	v_pk_mul_f32 v[40:41], v[6:7], v[56:57] op_sel:[0,1] op_sel_hi:[1,1]
	v_pk_fma_f32 v[38:39], v[8:9], v[58:59], v[38:39] op_sel_hi:[1,0,1]
	v_pk_fma_f32 v[40:41], v[8:9], v[58:59], v[40:41] op_sel:[0,1,0] op_sel_hi:[1,1,1]
	s_waitcnt lgkmcnt(4)
	v_pk_fma_f32 v[38:39], v[10:11], v[60:61], v[38:39] op_sel_hi:[1,0,1]
	v_pk_fma_f32 v[40:41], v[10:11], v[60:61], v[40:41] op_sel:[0,1,0] op_sel_hi:[1,1,1]
	v_pk_fma_f32 v[38:39], v[12:13], v[62:63], v[38:39] op_sel_hi:[1,0,1]
	v_pk_fma_f32 v[40:41], v[12:13], v[62:63], v[40:41] op_sel:[0,1,0] op_sel_hi:[1,1,1]
	s_waitcnt lgkmcnt(3)
	v_pk_fma_f32 v[38:39], v[14:15], v[64:65], v[38:39] op_sel_hi:[1,0,1]
	v_pk_fma_f32 v[40:41], v[14:15], v[64:65], v[40:41] op_sel:[0,1,0] op_sel_hi:[1,1,1]
	v_pk_fma_f32 v[38:39], v[16:17], v[66:67], v[38:39] op_sel_hi:[1,0,1]
	v_pk_fma_f32 v[40:41], v[16:17], v[66:67], v[40:41] op_sel:[0,1,0] op_sel_hi:[1,1,1]
	s_waitcnt lgkmcnt(2)
	v_pk_fma_f32 v[38:39], v[18:19], v[68:69], v[38:39] op_sel_hi:[1,0,1]
	v_pk_fma_f32 v[40:41], v[18:19], v[68:69], v[40:41] op_sel:[0,1,0] op_sel_hi:[1,1,1]
	v_pk_fma_f32 v[38:39], v[20:21], v[70:71], v[38:39] op_sel_hi:[1,0,1]
	v_pk_fma_f32 v[40:41], v[20:21], v[70:71], v[40:41] op_sel:[0,1,0] op_sel_hi:[1,1,1]
	s_waitcnt lgkmcnt(0)
	v_mul_f32_e32 v50, v76, v51
	v_add_f32_dpp v38, v38, v38 row_ror:8 row_mask:0xf bank_mask:0x3 bound_ctrl:1
	v_add_f32_dpp v39, v39, v39 row_ror:8 row_mask:0xf bank_mask:0x3 bound_ctrl:1
	v_add_f32_dpp v38, v40, v40 row_ror:8 row_mask:0xf bank_mask:0xc bound_ctrl:1
	v_add_f32_dpp v39, v41, v41 row_ror:8 row_mask:0xf bank_mask:0xc bound_ctrl:1
	ds_read_b128 v[80:83], v2 offset:40192
	v_add_f32_dpp v38, v38, v38 row_half_mirror row_mask:0xf bank_mask:0x5 bound_ctrl:1
	v_add_f32_dpp v38, v39, v39 row_half_mirror row_mask:0xf bank_mask:0xa bound_ctrl:1
	ds_read_b128 v[84:87], v2 offset:40448
	ds_read_b128 v[88:91], v2 offset:40704
	v_add_f32_dpp v38, v38, v38 quad_perm:[1,0,3,2] row_mask:0xf bank_mask:0xf bound_ctrl:1
	ds_read_b128 v[92:95], v2 offset:40960
	ds_read_b64 v[96:97], v3 offset:47104
	v_add_f32_dpp v38, v38, v38 quad_perm:[2,3,0,1] row_mask:0xf bank_mask:0xf bound_ctrl:1
	ds_read_b128 v[100:103], v1 offset:47472
	v_cmp_gt_f32_e32 vcc, 0x2b8cbccc, v50
	v_fmac_f32_dpp v72, -v38, v50 row_newbcast:0 row_mask:0xf bank_mask:0xf bound_ctrl:1
	v_fmac_f32_dpp v73, -v38, v50 row_newbcast:4 row_mask:0xf bank_mask:0xf bound_ctrl:1
	v_pk_mul_f32 v[44:45], v[72:73], v[76:77] op_sel:[0,1] op_sel_hi:[1,1]
	v_pk_mul_f32 v[48:49], v[44:45], v[78:79] op_sel_hi:[1,0]
	v_rcp_f32_e32 v52, v50
	s_add_u32 s14, s14, 0x1000
	s_addc_u32 s15, s15, 0
	v_fmac_f32_dpp v48, v38, v50 row_newbcast:8 row_mask:0xf bank_mask:0xf bound_ctrl:1
	v_fmac_f32_dpp v49, v38, v50 row_newbcast:12 row_mask:0xf bank_mask:0xf bound_ctrl:1
	s_cbranch_vccnz .Lgd2_rare2_6
.Lgd2_back2_6:
	v_cvt_pk_bf16_f32 v54, v48, v49
	v_pk_mul_f32 v[46:47], v[44:45], v[52:53] op_sel_hi:[1,0]
	v_pk_fma_f32 v[6:7], v[56:57], v[46:47], v[6:7] op_sel_hi:[0,1,1]
	v_pk_fma_f32 v[8:9], v[58:59], v[46:47], v[8:9] op_sel_hi:[0,1,1]
	v_pk_fma_f32 v[10:11], v[60:61], v[46:47], v[10:11] op_sel_hi:[0,1,1]
	v_pk_fma_f32 v[12:13], v[62:63], v[46:47], v[12:13] op_sel_hi:[0,1,1]
	v_pk_fma_f32 v[14:15], v[64:65], v[46:47], v[14:15] op_sel_hi:[0,1,1]
	v_pk_fma_f32 v[16:17], v[66:67], v[46:47], v[16:17] op_sel_hi:[0,1,1]
	v_pk_fma_f32 v[18:19], v[68:69], v[46:47], v[18:19] op_sel_hi:[0,1,1]
	v_pk_fma_f32 v[20:21], v[70:71], v[46:47], v[20:21] op_sel_hi:[0,1,1]
	global_store_dword v154, v54, s[14:15] offset:-4096
	s_waitcnt lgkmcnt(5)
	v_pk_mul_f32 v[38:39], v[6:7], v[80:81] op_sel_hi:[1,0]
	v_pk_mul_f32 v[40:41], v[6:7], v[80:81] op_sel:[0,1] op_sel_hi:[1,1]
	v_pk_fma_f32 v[38:39], v[8:9], v[82:83], v[38:39] op_sel_hi:[1,0,1]
	v_pk_fma_f32 v[40:41], v[8:9], v[82:83], v[40:41] op_sel:[0,1,0] op_sel_hi:[1,1,1]
	s_waitcnt lgkmcnt(4)
	v_pk_fma_f32 v[38:39], v[10:11], v[84:85], v[38:39] op_sel_hi:[1,0,1]
	v_pk_fma_f32 v[40:41], v[10:11], v[84:85], v[40:41] op_sel:[0,1,0] op_sel_hi:[1,1,1]
	v_pk_fma_f32 v[38:39], v[12:13], v[86:87], v[38:39] op_sel_hi:[1,0,1]
	v_pk_fma_f32 v[40:41], v[12:13], v[86:87], v[40:41] op_sel:[0,1,0] op_sel_hi:[1,1,1]
	s_waitcnt lgkmcnt(3)
	v_pk_fma_f32 v[38:39], v[14:15], v[88:89], v[38:39] op_sel_hi:[1,0,1]
	v_pk_fma_f32 v[40:41], v[14:15], v[88:89], v[40:41] op_sel:[0,1,0] op_sel_hi:[1,1,1]
	v_pk_fma_f32 v[38:39], v[16:17], v[90:91], v[38:39] op_sel_hi:[1,0,1]
	v_pk_fma_f32 v[40:41], v[16:17], v[90:91], v[40:41] op_sel:[0,1,0] op_sel_hi:[1,1,1]
	s_waitcnt lgkmcnt(2)
	v_pk_fma_f32 v[38:39], v[18:19], v[92:93], v[38:39] op_sel_hi:[1,0,1]
	v_pk_fma_f32 v[40:41], v[18:19], v[92:93], v[40:41] op_sel:[0,1,0] op_sel_hi:[1,1,1]
	v_pk_fma_f32 v[38:39], v[20:21], v[94:95], v[38:39] op_sel_hi:[1,0,1]
	v_pk_fma_f32 v[40:41], v[20:21], v[94:95], v[40:41] op_sel:[0,1,0] op_sel_hi:[1,1,1]
	s_waitcnt lgkmcnt(0)
	v_mul_f32_e32 v51, v100, v50
	v_add_f32_dpp v38, v38, v38 row_ror:8 row_mask:0xf bank_mask:0x3 bound_ctrl:1
	v_add_f32_dpp v39, v39, v39 row_ror:8 row_mask:0xf bank_mask:0x3 bound_ctrl:1
	v_add_f32_dpp v38, v40, v40 row_ror:8 row_mask:0xf bank_mask:0xc bound_ctrl:1
	v_add_f32_dpp v39, v41, v41 row_ror:8 row_mask:0xf bank_mask:0xc bound_ctrl:1
	ds_read_b128 v[56:59], v2 offset:256
	v_add_f32_dpp v38, v38, v38 row_half_mirror row_mask:0xf bank_mask:0x5 bound_ctrl:1
	v_add_f32_dpp v38, v39, v39 row_half_mirror row_mask:0xf bank_mask:0xa bound_ctrl:1
	ds_read_b128 v[60:63], v2 offset:512
	ds_read_b128 v[64:67], v2 offset:768
	v_add_f32_dpp v38, v38, v38 quad_perm:[1,0,3,2] row_mask:0xf bank_mask:0xf bound_ctrl:1
	ds_read_b128 v[68:71], v2 offset:1024
	ds_read_b64 v[72:73], v3 offset:12544
	v_add_f32_dpp v38, v38, v38 quad_perm:[2,3,0,1] row_mask:0xf bank_mask:0xf bound_ctrl:1
	ds_read_b128 v[76:79], v1 offset:14592
	v_cmp_gt_f32_e32 vcc, 0x2b8cbccc, v51
	v_fmac_f32_dpp v96, -v38, v51 row_newbcast:0 row_mask:0xf bank_mask:0xf bound_ctrl:1
	v_fmac_f32_dpp v97, -v38, v51 row_newbcast:4 row_mask:0xf bank_mask:0xf bound_ctrl:1
	v_pk_mul_f32 v[44:45], v[96:97], v[100:101] op_sel:[0,1] op_sel_hi:[1,1]
	v_pk_mul_f32 v[48:49], v[44:45], v[102:103] op_sel_hi:[1,0]
	v_rcp_f32_e32 v52, v51
	s_add_u32 s14, s14, 0x1000
	s_addc_u32 s15, s15, 0
	v_fmac_f32_dpp v48, v38, v51 row_newbcast:8 row_mask:0xf bank_mask:0xf bound_ctrl:1
	v_fmac_f32_dpp v49, v38, v51 row_newbcast:12 row_mask:0xf bank_mask:0xf bound_ctrl:1
	s_cbranch_vccnz .Lgd2_rare2_7
